# epilogue re-reads the finished row only (no gate loads); layer-0 adaLN1 row pass also uses LDS-staged weight vectors and DPP sums
# speedup vs baseline: 1.1121x; 1.0085x over previous
;     DEVI float* gw() const { return (float*)(ws + WS_GW); }
;     DEVI float* wsmall() const { return (float*)(ws + WS_WSMALL); }
; DEVI cfp_t inp(int i) { const __attribute__((address_space(4))) cfp_t* k = (const __attribute__((address_space(4))) cfp_t*)__builtin_amdgcn_kernarg_segment_ptr(); typedef const __attribute__((address_space(1))) float* gcfp_t; const gcfp_t r = *(const volatile __attribute__((address_space(4))) gcfp_t*)(k + i); return (cfp_t)r; }
; template <int WHICH> DEVI void adaln_apply(const P& p, int l, int r, int lane_in, float (&v)[16]) {
;     ...
;         const float* ws = p.wsmall() + (size_t)l * 12 * D + 16 * lane;
; template <int WHICH> DEVI void adaln_rows(const P& p, int l, int gw, int NGW, int lane, bool from_inputs = false) {
;     const float* xp_ = from_inputs ? inp(0) : p.x(); const float* xs_ = from_inputs ? inp(1) - (size_t)M_P * D : p.x();
;     float4 nx[4];
;     if (gw < M) {
; #pragma unroll
;         for (int q = 0; q < 4; ++q) nx[q] = ((const float4*)((gw < M_P ? xp_ : xs_) + (size_t)gw * D + 16 * lane))[q]; }
;     for (int r = gw; r < M; r += NGW) {
.LBB0_95:
	v_mov_b32_e32 v227, 0xc600000
	v_mov_b32_e32 v226, 0xd622000
	s_cmp_lg_u32 s6, 0
	v_writelane_b32 v253, s6, 41
	s_cbranch_scc1 .LBB0_163
	v_readlane_b32 s6, v252, 3
	s_mov_b64 s[2:3], s[74:75]
	s_mov_b64 s[4:5], s[72:73]
	v_mov_b32_e32 v1, v210
	s_mov_b32 s10, s95
	s_mov_b32 s14, s6
	s_mov_b32 s6, s68
	s_load_dwordx2 s[6:7], s[0:1], 0x0
	s_load_dwordx2 s[8:9], s[0:1], 0x8
	s_cmpk_gt_i32 s14, 0x43ff
	s_cbranch_scc1 .LBB0_118
	v_mov_b32_e32 v218, s85
	v_lshrrev_b32_e32 v219, 2, v218
	v_sub_u32_e32 v218, v218, v219
	v_lshl_add_u32 v218, v210, 4, v218
	v_add_u32_e32 v220, 0x14100, v218
	v_add_u32_e32 v218, 0x1f812100, v218
	v_add_u32_e32 v219, 0x1000, v218
	global_load_dwordx4 v[124:127], v218, s[74:75] offset:0
	global_load_dwordx4 v[128:131], v218, s[74:75] offset:1024
	global_load_dwordx4 v[132:135], v218, s[74:75] offset:2048
	global_load_dwordx4 v[136:139], v218, s[74:75] offset:3072
	global_load_dwordx4 v[140:143], v219, s[74:75] offset:0
	global_load_dwordx4 v[144:147], v219, s[74:75] offset:1024
	s_waitcnt vmcnt(0)
	ds_write_b128 v220, v[124:127] offset:0
	ds_write_b128 v220, v[128:131] offset:1024
	ds_write_b128 v220, v[132:135] offset:2048
	ds_write_b128 v220, v[136:139] offset:3072
	ds_write_b128 v220, v[140:143] offset:4096
	ds_write_b128 v220, v[144:147] offset:5120
	s_waitcnt lgkmcnt(0)
	s_barrier
	s_waitcnt lgkmcnt(0)
	s_add_u32 s26, s8, 0xfc000000
	s_addc_u32 s27, s9, -1
	s_cmpk_lt_i32 s14, 0x4000
	s_cselect_b32 s11, s7, s27
	s_cselect_b32 s12, s6, s26
	s_ashr_i32 s15, s14, 31
	s_lshl_b64 s[8:9], s[14:15], 12
	v_lshlrev_b32_e32 v2, 4, v1
	s_add_u32 s8, s12, s8
	v_ashrrev_i32_e32 v3, 31, v2
	s_addc_u32 s9, s11, s9
	v_lshlrev_b64 v[2:3], 2, v[2:3]
	v_lshl_add_u64 v[4:5], s[8:9], 0, v[2:3]
	global_load_dwordx4 v[34:37], v[4:5], off offset:48
	global_load_dwordx4 v[38:41], v[4:5], off offset:32
	global_load_dwordx4 v[42:45], v[4:5], off offset:16
	global_load_dwordx4 v[46:49], v[4:5], off
	s_waitcnt vmcnt(0)
	v_mov_b64_e32 v[10:11], s[2:3]
	v_mov_b32_e32 v12, 0xc000
	v_mad_i64_i32 v[6:7], s[8:9], s10, 18, 0
	v_mad_i64_i32 v[10:11], s[8:9], s10, v12, v[10:11]
	s_add_u32 s30, s2, 0x4000
	s_mov_b64 s[8:9], 0x1f812100
	s_addc_u32 s31, s3, 0
	v_lshl_add_u64 v[56:57], v[10:11], 0, s[8:9]
	s_lshl_b64 s[8:9], s[14:15], 5
	s_add_u32 s40, s8, 0xacda100
	v_ashrrev_i32_e64 v5, 31, s10
	v_mov_b32_e32 v4, s10
	s_addc_u32 s41, s9, 0
	s_add_i32 s12, s34, s14
	v_lshlrev_b64 v[54:55], 10, v[4:5]
	v_readfirstlane_b32 s28, v6
	v_lshlrev_b32_e64 v6, 2, s10
	v_lshlrev_b64 v[4:5], 18, v[4:5]
	v_lshlrev_b32_e64 v8, 3, s10
	s_ashr_i32 s13, s12, 31
	v_readfirstlane_b32 s29, v7
	v_ashrrev_i32_e32 v7, 31, v6
	v_ashrrev_i32_e32 v9, 31, v8
	v_lshl_add_u64 v[4:5], s[4:5], 0, v[4:5]
	s_mov_b64 s[10:11], 0xc400000
	s_lshl_b64 s[12:13], s[12:13], 12
	s_lshl_b64 s[8:9], s[14:15], 4
	v_lshl_add_u64 v[58:59], v[4:5], 0, s[10:11]
	s_lshl_b64 s[10:11], s[14:15], 11
	v_lshl_add_u64 v[60:61], s[12:13], 0, v[2:3]
	v_lshlrev_b64 v[62:63], 2, v[6:7]
	v_lshlrev_b64 v[64:65], 2, v[8:9]
	s_branch .LBB0_100

;     DEVI float* mod() const { return (float*)(ws + WS_MOD); }
;     DEVI float* rstd() const { return (float*)(ws + WS_RSTD); }
;     DEVI bf16_t* hb() const { return (bf16_t*)(ws + WS_HB); }
;     DEVI float* wsmall() const { return (float*)(ws + WS_WSMALL); }
; DEVI unsigned pk2bf(float lo, float hi) { unsigned r; asm volatile("v_cvt_pk_bf16_f32 %0, %1, %2" : "=v"(r) : "v"(lo), "v"(hi)); return r; }
; template <int WHICH> DEVI void adaln_apply(const P& p, int l, int r, int lane_in, float (&v)[16]) {
;     ...
;     const float rstd = rsqrtf(wave_sum(ss) * (1.f / D) + EPS);
;     const float* md = p.mod() + ((size_t)l * NSEQ + row_seq(r)) * 6144 + 16 * lane;
; #pragma unroll
;     for (int q = 0; q < 4; ++q) {
;         const float4 gg = *(const float4*)(g + 4 * q), sc = *(const float4*)(md + osc + 4 * q), sh = *(const float4*)(md + osh + 4 * q);
;         v[4 * q] = v[4 * q] * rstd * gg.x * (1.f + sc.x) + sh.x; v[4 * q + 1] = v[4 * q + 1] * rstd * gg.y * (1.f + sc.y) + sh.y;
;         v[4 * q + 2] = v[4 * q + 2] * rstd * gg.z * (1.f + sc.z) + sh.z; v[4 * q + 3] = v[4 * q + 3] * rstd * gg.w * (1.f + sc.w) + sh.w;
;     }
;     u32x4_t* ob = (u32x4_t*)(p.hb() + (size_t)r * D + 16 * lane);
;     ob[0] = (u32x4_t){pk2bf(v[0], v[1]), pk2bf(v[2], v[3]), pk2bf(v[4], v[5]), pk2bf(v[6], v[7])};
;     ob[1] = (u32x4_t){pk2bf(v[8], v[9]), pk2bf(v[10], v[11]), pk2bf(v[12], v[13]), pk2bf(v[14], v[15])};
;     ...
;         const float* ws = p.wsmall() + (size_t)l * 12 * D + 16 * lane;
;         float dot[12];
; #pragma unroll
;         for (int jj = 0; jj < 12; ++jj) { float a = 0.f;
; #pragma unroll
;             for (int q = 0; q < 4; ++q) { const float4 w = *(const float4*)(ws + (size_t)jj * D + 4 * q); a += v[4 * q] * w.x + v[4 * q + 1] * w.y + v[4 * q + 2] * w.z + v[4 * q + 3] * w.w; }
.LBB0_106:
	v_lshlrev_b64 v[18:19], 2, v[54:55]
	v_lshl_add_u64 v[18:19], s[18:19], 0, v[18:19]
	s_ashr_i32 s18, s15, 31
	s_add_u32 s15, s28, s15
	s_addc_u32 s18, s29, s18
	s_mulk_i32 s18, 0x6000
	s_mul_hi_u32 s19, s15, 0x6000
	v_lshlrev_b32_e32 v106, 4, v68
	s_add_i32 s19, s19, s18
	s_mulk_i32 s15, 0x6000
	v_ashrrev_i32_e32 v107, 31, v106
	s_add_u32 s18, s30, s15
	v_lshlrev_b64 v[50:51], 2, v[106:107]
	s_addc_u32 s19, s31, s19
	v_lshl_add_u64 v[18:19], v[18:19], 0, v[50:51]
	v_lshl_add_u64 v[22:23], s[18:19], 0, v[50:51]
	s_movk_i32 s15, 0x1000
	global_load_dwordx4 v[74:77], v[18:19], off offset:16
	global_load_dwordx4 v[78:81], v[18:19], off
	global_load_dwordx4 v[82:85], v[18:19], off offset:48
	global_load_dwordx4 v[86:89], v[18:19], off offset:32
	v_add_co_u32_e32 v18, vcc, s15, v22
	s_mov_b64 s[22:23], 0x1000
	s_nop 0
	v_addc_co_u32_e32 v19, vcc, 0, v23, vcc
	global_load_dwordx4 v[90:93], v[18:19], off
	v_lshl_add_u64 v[24:25], v[22:23], 0, s[22:23]
	global_load_dwordx4 v[94:97], v[24:25], off offset:16
	global_load_dwordx4 v[98:101], v[24:25], off offset:32
	global_load_dwordx4 v[30:33], v[22:23], off
	global_load_dwordx4 v[26:29], v[22:23], off offset:16
	global_load_dwordx4 v[18:21], v[22:23], off offset:32
	global_load_dwordx4 v[102:105], v[24:25], off offset:48
	s_nop 0
	global_load_dwordx4 v[22:25], v[22:23], off offset:48
	s_waitcnt lgkmcnt(0)
	v_add_f32_e32 v52, v52, v53
	v_fmamk_f32 v52, v52, 0x3a800000, v211
	s_mov_b32 s15, 0x800000
	v_mul_f32_e32 v53, 0x4b800000, v52
	v_cmp_gt_f32_e32 vcc, s15, v52
	s_add_u32 s18, s2, s10
	s_addc_u32 s19, s3, s11
	v_cndmask_b32_e32 v52, v52, v53, vcc
	v_rsq_f32_e32 v52, v52
	s_movk_i32 s15, 0x2000
	v_mul_f32_e32 v53, 0x45800000, v52
	v_cndmask_b32_e32 v52, v52, v53, vcc
	v_mul_f32_e32 v46, v46, v52
	v_mul_f32_e32 v42, v42, v52
	v_mul_f32_e32 v38, v38, v52
	v_mul_f32_e32 v34, v34, v52
	v_mul_f32_e32 v47, v47, v52
	v_mul_f32_e32 v43, v43, v52
	v_mul_f32_e32 v39, v39, v52
	v_mul_f32_e32 v48, v48, v52
	v_mul_f32_e32 v49, v49, v52
	v_mul_f32_e32 v44, v44, v52
	v_mul_f32_e32 v45, v45, v52
	v_mul_f32_e32 v40, v40, v52
	v_mul_f32_e32 v41, v41, v52
	s_waitcnt vmcnt(11)
	v_mul_f32_e32 v42, v42, v74
	s_waitcnt vmcnt(10)
	v_mul_f32_e32 v46, v46, v78
	s_waitcnt vmcnt(8)
	v_mul_f32_e32 v38, v38, v86
	v_mul_f32_e32 v34, v34, v82
	s_waitcnt vmcnt(6)
	v_add_f32_e32 v78, 1.0, v94
	s_waitcnt vmcnt(5)
	v_add_f32_e32 v82, 1.0, v98
	v_mul_f32_e32 v47, v47, v79
	v_mul_f32_e32 v43, v43, v75
	v_add_f32_e32 v53, 1.0, v90
	s_waitcnt vmcnt(4)
	v_fma_f32 v74, v46, v53, v30
	s_waitcnt vmcnt(3)
	v_fma_f32 v30, v42, v78, v26
	s_waitcnt vmcnt(2)
	v_fma_f32 v26, v38, v82, v18
	s_waitcnt vmcnt(1)
	v_add_f32_e32 v18, 1.0, v102
	v_mul_f32_e32 v39, v39, v87
	v_add_f32_e32 v75, 1.0, v91
	v_add_f32_e32 v79, 1.0, v95
	v_add_f32_e32 v86, 1.0, v99
	s_waitcnt vmcnt(0)
	v_fma_f32 v22, v34, v18, v22
	v_mul_f32_e32 v18, v35, v52
	v_fma_f32 v75, v47, v75, v31
	v_fma_f32 v31, v43, v79, v27
	v_fma_f32 v27, v39, v86, v19
	v_mul_f32_e32 v18, v18, v83
	v_add_f32_e32 v19, 1.0, v103
	v_fma_f32 v23, v18, v19, v23
	v_mul_f32_e32 v18, v36, v52
	v_mul_f32_e32 v18, v18, v84
	v_add_f32_e32 v19, 1.0, v104
	v_fma_f32 v24, v18, v19, v24
	v_mul_f32_e32 v18, v37, v52
	v_mul_f32_e32 v18, v18, v85
	v_add_f32_e32 v19, 1.0, v105
	v_fmac_f32_e32 v25, v18, v19
	v_lshl_add_u64 v[18:19], v[106:107], 1, s[18:19]
	v_mul_f32_e32 v48, v48, v80
	v_mul_f32_e32 v49, v49, v81
	v_mul_f32_e32 v44, v44, v76
	v_mul_f32_e32 v45, v45, v77
	v_add_f32_e32 v76, 1.0, v92
	v_add_f32_e32 v77, 1.0, v93
	v_add_f32_e32 v80, 1.0, v96
	v_add_f32_e32 v81, 1.0, v97
	v_add_co_u32_e32 v18, vcc, s82, v18
	v_mul_f32_e32 v40, v40, v88
	v_mul_f32_e32 v41, v41, v89
	v_add_f32_e32 v87, 1.0, v100
	v_add_f32_e32 v88, 1.0, v101
	v_fma_f32 v32, v48, v76, v32
	v_fmac_f32_e32 v33, v49, v77
	v_fma_f32 v28, v44, v80, v28
	v_fmac_f32_e32 v29, v45, v81
	v_cvt_pk_bf16_f32 v34, v74, v75
	v_cvt_pk_bf16_f32 v35, v32, v33
	v_cvt_pk_bf16_f32 v36, v30, v31
	v_cvt_pk_bf16_f32 v37, v28, v29
	v_addc_co_u32_e32 v19, vcc, 0, v19, vcc
	v_fma_f32 v20, v40, v87, v20
	v_fmac_f32_e32 v21, v41, v88
	global_store_dwordx4 v[18:19], v[34:37], off offset:256
	s_nop 1
	v_cvt_pk_bf16_f32 v34, v26, v27
	v_cvt_pk_bf16_f32 v35, v20, v21
	v_cvt_pk_bf16_f32 v36, v22, v23
	v_cvt_pk_bf16_f32 v37, v24, v25
	global_store_dwordx4 v[18:19], v[34:37], off offset:272
	v_mov_b32_e32 v219, 0x14100
	v_lshl_add_u32 v218, v68, 6, v219
	v_mov_b32_e32 v216, 0
	v_mov_b32_e32 v217, 0
	ds_read_b128 v[124:127], v218 offset:0
	ds_read_b128 v[128:131], v218 offset:16
	ds_read_b128 v[132:135], v218 offset:32
	ds_read_b128 v[136:139], v218 offset:48
	ds_read_b128 v[140:143], v218 offset:4096
	ds_read_b128 v[144:147], v218 offset:4112
	ds_read_b128 v[148:151], v218 offset:4128
	ds_read_b128 v[152:155], v218 offset:4144
	ds_read_b128 v[156:159], v218 offset:8192
	ds_read_b128 v[160:163], v218 offset:8208
	ds_read_b128 v[164:167], v218 offset:8224
	ds_read_b128 v[168:171], v218 offset:8240
	ds_read_b128 v[172:175], v218 offset:12288
	ds_read_b128 v[180:183], v218 offset:12304
	ds_read_b128 v[184:187], v218 offset:12320
	ds_read_b128 v[188:191], v218 offset:12336
	s_waitcnt lgkmcnt(0)
; template <int WHICH> DEVI void adaln_apply(const P& p, int l, int r, int lane_in, float (&v)[16]) {
;     ...
;         for (int jj = 0; jj < 12; ++jj) { float a = 0.f;
; #pragma unroll
;             for (int q = 0; q < 4; ++q) { const float4 w = *(const float4*)(ws + (size_t)jj * D + 4 * q); a += v[4 * q] * w.x + v[4 * q + 1] * w.y + v[4 * q + 2] * w.z + v[4 * q + 3] * w.w; }
	v_mul_f32_e32 v192, v74, v124
	v_mul_f32_e32 v193, v74, v140
	v_mul_f32_e32 v194, v74, v156
	v_mul_f32_e32 v195, v74, v172
	v_fmac_f32_e32 v192, v75, v125
	v_fmac_f32_e32 v193, v75, v141
	v_fmac_f32_e32 v194, v75, v157
	v_fmac_f32_e32 v195, v75, v173
	v_fmac_f32_e32 v192, v32, v126
	v_fmac_f32_e32 v193, v32, v142
	v_fmac_f32_e32 v194, v32, v158
	v_fmac_f32_e32 v195, v32, v174
	v_fmac_f32_e32 v192, v33, v127
	v_fmac_f32_e32 v193, v33, v143
	v_fmac_f32_e32 v194, v33, v159
	v_fmac_f32_e32 v195, v33, v175
	v_fmac_f32_e32 v192, v30, v128
	v_fmac_f32_e32 v193, v30, v144
	v_fmac_f32_e32 v194, v30, v160
	v_fmac_f32_e32 v195, v30, v180
	v_fmac_f32_e32 v192, v31, v129
	v_fmac_f32_e32 v193, v31, v145
	v_fmac_f32_e32 v194, v31, v161
	v_fmac_f32_e32 v195, v31, v181
	v_fmac_f32_e32 v192, v28, v130
	v_fmac_f32_e32 v193, v28, v146
	v_fmac_f32_e32 v194, v28, v162
	v_fmac_f32_e32 v195, v28, v182
	v_fmac_f32_e32 v192, v29, v131
	v_fmac_f32_e32 v193, v29, v147
	v_fmac_f32_e32 v194, v29, v163
	v_fmac_f32_e32 v195, v29, v183
	v_fmac_f32_e32 v192, v26, v132
	v_fmac_f32_e32 v193, v26, v148
	v_fmac_f32_e32 v194, v26, v164
	v_fmac_f32_e32 v195, v26, v184
	v_fmac_f32_e32 v192, v27, v133
	v_fmac_f32_e32 v193, v27, v149
	v_fmac_f32_e32 v194, v27, v165
	v_fmac_f32_e32 v195, v27, v185
	v_fmac_f32_e32 v192, v20, v134
	v_fmac_f32_e32 v193, v20, v150
	v_fmac_f32_e32 v194, v20, v166
	v_fmac_f32_e32 v195, v20, v186
	v_fmac_f32_e32 v192, v21, v135
	v_fmac_f32_e32 v193, v21, v151
	v_fmac_f32_e32 v194, v21, v167
	v_fmac_f32_e32 v195, v21, v187
	v_fmac_f32_e32 v192, v22, v136
	v_fmac_f32_e32 v193, v22, v152
	v_fmac_f32_e32 v194, v22, v168
	v_fmac_f32_e32 v195, v22, v188
	v_fmac_f32_e32 v192, v23, v137
	v_fmac_f32_e32 v193, v23, v153
	v_fmac_f32_e32 v194, v23, v169
	v_fmac_f32_e32 v195, v23, v189
	v_fmac_f32_e32 v192, v24, v138
	v_fmac_f32_e32 v193, v24, v154
	v_fmac_f32_e32 v194, v24, v170
	v_fmac_f32_e32 v195, v24, v190
	v_fmac_f32_e32 v192, v25, v139
	v_fmac_f32_e32 v193, v25, v155
	v_fmac_f32_e32 v194, v25, v171
	v_fmac_f32_e32 v195, v25, v191
	ds_read_b128 v[124:127], v218 offset:16384
	ds_read_b128 v[128:131], v218 offset:16400
	ds_read_b128 v[132:135], v218 offset:16416
	ds_read_b128 v[136:139], v218 offset:16432
	ds_read_b128 v[140:143], v218 offset:20480
	ds_read_b128 v[144:147], v218 offset:20496
	ds_read_b128 v[148:151], v218 offset:20512
	ds_read_b128 v[152:155], v218 offset:20528
	ds_read_b128 v[156:159], v218 offset:24576
	ds_read_b128 v[160:163], v218 offset:24592
	ds_read_b128 v[164:167], v218 offset:24608
	ds_read_b128 v[168:171], v218 offset:24624
	ds_read_b128 v[172:175], v218 offset:28672
	ds_read_b128 v[180:183], v218 offset:28688
	ds_read_b128 v[184:187], v218 offset:28704
	ds_read_b128 v[188:191], v218 offset:28720
	s_waitcnt lgkmcnt(0)
	v_mul_f32_e32 v196, v74, v124
	v_mul_f32_e32 v197, v74, v140
	v_mul_f32_e32 v198, v74, v156
	v_mul_f32_e32 v199, v74, v172
	v_fmac_f32_e32 v196, v75, v125
	v_fmac_f32_e32 v197, v75, v141
	v_fmac_f32_e32 v198, v75, v157
	v_fmac_f32_e32 v199, v75, v173
	v_fmac_f32_e32 v196, v32, v126
	v_fmac_f32_e32 v197, v32, v142
	v_fmac_f32_e32 v198, v32, v158
	v_fmac_f32_e32 v199, v32, v174
	v_fmac_f32_e32 v196, v33, v127
	v_fmac_f32_e32 v197, v33, v143
	v_fmac_f32_e32 v198, v33, v159
	v_fmac_f32_e32 v199, v33, v175
	v_fmac_f32_e32 v196, v30, v128
	v_fmac_f32_e32 v197, v30, v144
	v_fmac_f32_e32 v198, v30, v160
	v_fmac_f32_e32 v199, v30, v180
	v_fmac_f32_e32 v196, v31, v129
	v_fmac_f32_e32 v197, v31, v145
	v_fmac_f32_e32 v198, v31, v161
	v_fmac_f32_e32 v199, v31, v181
	v_fmac_f32_e32 v196, v28, v130
	v_fmac_f32_e32 v197, v28, v146
	v_fmac_f32_e32 v198, v28, v162
	v_fmac_f32_e32 v199, v28, v182
	v_fmac_f32_e32 v196, v29, v131
	v_fmac_f32_e32 v197, v29, v147
	v_fmac_f32_e32 v198, v29, v163
	v_fmac_f32_e32 v199, v29, v183
	v_fmac_f32_e32 v196, v26, v132
	v_fmac_f32_e32 v197, v26, v148
	v_fmac_f32_e32 v198, v26, v164
	v_fmac_f32_e32 v199, v26, v184
	v_fmac_f32_e32 v196, v27, v133
	v_fmac_f32_e32 v197, v27, v149
	v_fmac_f32_e32 v198, v27, v165
	v_fmac_f32_e32 v199, v27, v185
	v_fmac_f32_e32 v196, v20, v134
	v_fmac_f32_e32 v197, v20, v150
	v_fmac_f32_e32 v198, v20, v166
	v_fmac_f32_e32 v199, v20, v186
	v_fmac_f32_e32 v196, v21, v135
	v_fmac_f32_e32 v197, v21, v151
	v_fmac_f32_e32 v198, v21, v167
	v_fmac_f32_e32 v199, v21, v187
	v_fmac_f32_e32 v196, v22, v136
	v_fmac_f32_e32 v197, v22, v152
	v_fmac_f32_e32 v198, v22, v168
	v_fmac_f32_e32 v199, v22, v188
	v_fmac_f32_e32 v196, v23, v137
	v_fmac_f32_e32 v197, v23, v153
	v_fmac_f32_e32 v198, v23, v169
	v_fmac_f32_e32 v199, v23, v189
	v_fmac_f32_e32 v196, v24, v138
	v_fmac_f32_e32 v197, v24, v154
	v_fmac_f32_e32 v198, v24, v170
	v_fmac_f32_e32 v199, v24, v190
	v_fmac_f32_e32 v196, v25, v139
	v_fmac_f32_e32 v197, v25, v155
	v_fmac_f32_e32 v198, v25, v171
	v_fmac_f32_e32 v199, v25, v191
	ds_read_b128 v[124:127], v218 offset:32768
	ds_read_b128 v[128:131], v218 offset:32784
	ds_read_b128 v[132:135], v218 offset:32800
	ds_read_b128 v[136:139], v218 offset:32816
	ds_read_b128 v[140:143], v218 offset:36864
	ds_read_b128 v[144:147], v218 offset:36880
	ds_read_b128 v[148:151], v218 offset:36896
	ds_read_b128 v[152:155], v218 offset:36912
	ds_read_b128 v[156:159], v218 offset:40960
	ds_read_b128 v[160:163], v218 offset:40976
	ds_read_b128 v[164:167], v218 offset:40992
	ds_read_b128 v[168:171], v218 offset:41008
	ds_read_b128 v[172:175], v218 offset:45056
	ds_read_b128 v[180:183], v218 offset:45072
	ds_read_b128 v[184:187], v218 offset:45088
	ds_read_b128 v[188:191], v218 offset:45104
	s_waitcnt lgkmcnt(0)
; DEVI float wave_sum(float v) {
; #pragma unroll
;     for (int o = 1; o < 64; o <<= 1) v += __shfl_xor(v, o);
;     return v;
; template <int WHICH> DEVI void adaln_apply(const P& p, int l, int r, int lane_in, float (&v)[16]) {
;     ...
;         for (int jj = 0; jj < 12; ++jj) { float a = 0.f;
; #pragma unroll
;             for (int q = 0; q < 4; ++q) { const float4 w = *(const float4*)(ws + (size_t)jj * D + 4 * q); a += v[4 * q] * w.x + v[4 * q + 1] * w.y + v[4 * q + 2] * w.z + v[4 * q + 3] * w.w; }
;             dot[jj] = wave_sum(a); }
	v_mul_f32_e32 v200, v74, v124
	v_mul_f32_e32 v201, v74, v140
	v_mul_f32_e32 v202, v74, v156
	v_mul_f32_e32 v203, v74, v172
	v_fmac_f32_e32 v200, v75, v125
	v_fmac_f32_e32 v201, v75, v141
	v_fmac_f32_e32 v202, v75, v157
	v_fmac_f32_e32 v203, v75, v173
	v_fmac_f32_e32 v200, v32, v126
	v_fmac_f32_e32 v201, v32, v142
	v_fmac_f32_e32 v202, v32, v158
	v_fmac_f32_e32 v203, v32, v174
	v_fmac_f32_e32 v200, v33, v127
	v_fmac_f32_e32 v201, v33, v143
	v_fmac_f32_e32 v202, v33, v159
	v_fmac_f32_e32 v203, v33, v175
	v_fmac_f32_e32 v200, v30, v128
	v_fmac_f32_e32 v201, v30, v144
	v_fmac_f32_e32 v202, v30, v160
	v_fmac_f32_e32 v203, v30, v180
	v_fmac_f32_e32 v200, v31, v129
	v_fmac_f32_e32 v201, v31, v145
	v_fmac_f32_e32 v202, v31, v161
	v_fmac_f32_e32 v203, v31, v181
	v_fmac_f32_e32 v200, v28, v130
	v_fmac_f32_e32 v201, v28, v146
	v_fmac_f32_e32 v202, v28, v162
	v_fmac_f32_e32 v203, v28, v182
	v_fmac_f32_e32 v200, v29, v131
	v_fmac_f32_e32 v201, v29, v147
	v_fmac_f32_e32 v202, v29, v163
	v_fmac_f32_e32 v203, v29, v183
	v_fmac_f32_e32 v200, v26, v132
	v_fmac_f32_e32 v201, v26, v148
	v_fmac_f32_e32 v202, v26, v164
	v_fmac_f32_e32 v203, v26, v184
	v_fmac_f32_e32 v200, v27, v133
	v_fmac_f32_e32 v201, v27, v149
	v_fmac_f32_e32 v202, v27, v165
	v_fmac_f32_e32 v203, v27, v185
	v_fmac_f32_e32 v200, v20, v134
	v_fmac_f32_e32 v201, v20, v150
	v_fmac_f32_e32 v202, v20, v166
	v_fmac_f32_e32 v203, v20, v186
	v_fmac_f32_e32 v200, v21, v135
	v_fmac_f32_e32 v201, v21, v151
	v_fmac_f32_e32 v202, v21, v167
	v_fmac_f32_e32 v203, v21, v187
	v_fmac_f32_e32 v200, v22, v136
	v_fmac_f32_e32 v201, v22, v152
	v_fmac_f32_e32 v202, v22, v168
	v_fmac_f32_e32 v203, v22, v188
	v_fmac_f32_e32 v200, v23, v137
	v_fmac_f32_e32 v201, v23, v153
	v_fmac_f32_e32 v202, v23, v169
	v_fmac_f32_e32 v203, v23, v189
	v_fmac_f32_e32 v200, v24, v138
	v_fmac_f32_e32 v201, v24, v154
	v_fmac_f32_e32 v202, v24, v170
	v_fmac_f32_e32 v203, v24, v190
	v_fmac_f32_e32 v200, v25, v139
	v_fmac_f32_e32 v201, v25, v155
	v_fmac_f32_e32 v202, v25, v171
	v_fmac_f32_e32 v203, v25, v191
	s_nop 1
	v_add_f32_dpp v192, v192, v192 quad_perm:[1,0,3,2] row_mask:0xf bank_mask:0xf
	v_add_f32_dpp v193, v193, v193 quad_perm:[1,0,3,2] row_mask:0xf bank_mask:0xf
	v_add_f32_dpp v194, v194, v194 quad_perm:[1,0,3,2] row_mask:0xf bank_mask:0xf
	v_add_f32_dpp v195, v195, v195 quad_perm:[1,0,3,2] row_mask:0xf bank_mask:0xf
	v_add_f32_dpp v196, v196, v196 quad_perm:[1,0,3,2] row_mask:0xf bank_mask:0xf
	v_add_f32_dpp v197, v197, v197 quad_perm:[1,0,3,2] row_mask:0xf bank_mask:0xf
	v_add_f32_dpp v198, v198, v198 quad_perm:[1,0,3,2] row_mask:0xf bank_mask:0xf
	v_add_f32_dpp v199, v199, v199 quad_perm:[1,0,3,2] row_mask:0xf bank_mask:0xf
	v_add_f32_dpp v200, v200, v200 quad_perm:[1,0,3,2] row_mask:0xf bank_mask:0xf
	v_add_f32_dpp v201, v201, v201 quad_perm:[1,0,3,2] row_mask:0xf bank_mask:0xf
	v_add_f32_dpp v202, v202, v202 quad_perm:[1,0,3,2] row_mask:0xf bank_mask:0xf
	v_add_f32_dpp v203, v203, v203 quad_perm:[1,0,3,2] row_mask:0xf bank_mask:0xf
	v_add_f32_dpp v192, v192, v192 quad_perm:[2,3,0,1] row_mask:0xf bank_mask:0xf
	v_add_f32_dpp v193, v193, v193 quad_perm:[2,3,0,1] row_mask:0xf bank_mask:0xf
	v_add_f32_dpp v194, v194, v194 quad_perm:[2,3,0,1] row_mask:0xf bank_mask:0xf
	v_add_f32_dpp v195, v195, v195 quad_perm:[2,3,0,1] row_mask:0xf bank_mask:0xf
	v_add_f32_dpp v196, v196, v196 quad_perm:[2,3,0,1] row_mask:0xf bank_mask:0xf
	v_add_f32_dpp v197, v197, v197 quad_perm:[2,3,0,1] row_mask:0xf bank_mask:0xf
	v_add_f32_dpp v198, v198, v198 quad_perm:[2,3,0,1] row_mask:0xf bank_mask:0xf
	v_add_f32_dpp v199, v199, v199 quad_perm:[2,3,0,1] row_mask:0xf bank_mask:0xf
	v_add_f32_dpp v200, v200, v200 quad_perm:[2,3,0,1] row_mask:0xf bank_mask:0xf
	v_add_f32_dpp v201, v201, v201 quad_perm:[2,3,0,1] row_mask:0xf bank_mask:0xf
	v_add_f32_dpp v202, v202, v202 quad_perm:[2,3,0,1] row_mask:0xf bank_mask:0xf
	v_add_f32_dpp v203, v203, v203 quad_perm:[2,3,0,1] row_mask:0xf bank_mask:0xf
	v_add_f32_dpp v192, v192, v192 row_half_mirror row_mask:0xf bank_mask:0xf
	v_add_f32_dpp v193, v193, v193 row_half_mirror row_mask:0xf bank_mask:0xf
	v_add_f32_dpp v194, v194, v194 row_half_mirror row_mask:0xf bank_mask:0xf
	v_add_f32_dpp v195, v195, v195 row_half_mirror row_mask:0xf bank_mask:0xf
	v_add_f32_dpp v196, v196, v196 row_half_mirror row_mask:0xf bank_mask:0xf
	v_add_f32_dpp v197, v197, v197 row_half_mirror row_mask:0xf bank_mask:0xf
	v_add_f32_dpp v198, v198, v198 row_half_mirror row_mask:0xf bank_mask:0xf
	v_add_f32_dpp v199, v199, v199 row_half_mirror row_mask:0xf bank_mask:0xf
	v_add_f32_dpp v200, v200, v200 row_half_mirror row_mask:0xf bank_mask:0xf
	v_add_f32_dpp v201, v201, v201 row_half_mirror row_mask:0xf bank_mask:0xf
	v_add_f32_dpp v202, v202, v202 row_half_mirror row_mask:0xf bank_mask:0xf
	v_add_f32_dpp v203, v203, v203 row_half_mirror row_mask:0xf bank_mask:0xf
	v_add_f32_dpp v192, v192, v192 row_mirror row_mask:0xf bank_mask:0xf
	v_add_f32_dpp v193, v193, v193 row_mirror row_mask:0xf bank_mask:0xf
	v_add_f32_dpp v194, v194, v194 row_mirror row_mask:0xf bank_mask:0xf
	v_add_f32_dpp v195, v195, v195 row_mirror row_mask:0xf bank_mask:0xf
	v_add_f32_dpp v196, v196, v196 row_mirror row_mask:0xf bank_mask:0xf
	v_add_f32_dpp v197, v197, v197 row_mirror row_mask:0xf bank_mask:0xf
	v_add_f32_dpp v198, v198, v198 row_mirror row_mask:0xf bank_mask:0xf
	v_add_f32_dpp v199, v199, v199 row_mirror row_mask:0xf bank_mask:0xf
	v_add_f32_dpp v200, v200, v200 row_mirror row_mask:0xf bank_mask:0xf
	v_add_f32_dpp v201, v201, v201 row_mirror row_mask:0xf bank_mask:0xf
	v_add_f32_dpp v202, v202, v202 row_mirror row_mask:0xf bank_mask:0xf
;     DEVI float* dt() const { return (float*)(ws + WS_DT); }
;     DEVI float* logf() const { return (float*)(ws + WS_LOGF); }
; DEVI float softplus_f(float x) { return x > 20.f ? x : log1pf(expf(x)); }
; DEVI float wave_sum(float v) {
; #pragma unroll
;     for (int o = 1; o < 64; o <<= 1) v += __shfl_xor(v, o);
;     return v;
; template <int WHICH> DEVI void adaln_apply(const P& p, int l, int r, int lane_in, float (&v)[16]) {
;     ...
;         if (lane < 8) {
;             float d = dot[0];
; #pragma unroll
;             for (int jj = 1; jj < 8; ++jj) d = (lane == jj) ? dot[jj] : d;
;             p.dt()[(size_t)r * 8 + lane] = softplus_f(d + dtb[lane]);
;         } else if (lane < 12) {
;             const int hd = lane - 8; float d = dot[8];
; #pragma unroll
;             for (int jj = 9; jj < 12; ++jj) d = (lane == jj) ? dot[jj] : d;
;             const float lf = -softplus_f(-(d + fb[hd]));
;             p.logf()[(size_t)r * 4 + hd] = lf;
	v_add_f32_dpp v203, v203, v203 row_mirror row_mask:0xf bank_mask:0xf
	v_add_f32_dpp v192, v192, v192 row_bcast:15 row_mask:0xa bank_mask:0xf
	v_add_f32_dpp v193, v193, v193 row_bcast:15 row_mask:0xa bank_mask:0xf
	v_add_f32_dpp v194, v194, v194 row_bcast:15 row_mask:0xa bank_mask:0xf
	v_add_f32_dpp v195, v195, v195 row_bcast:15 row_mask:0xa bank_mask:0xf
	v_add_f32_dpp v196, v196, v196 row_bcast:15 row_mask:0xa bank_mask:0xf
	v_add_f32_dpp v197, v197, v197 row_bcast:15 row_mask:0xa bank_mask:0xf
	v_add_f32_dpp v198, v198, v198 row_bcast:15 row_mask:0xa bank_mask:0xf
	v_add_f32_dpp v199, v199, v199 row_bcast:15 row_mask:0xa bank_mask:0xf
	v_add_f32_dpp v200, v200, v200 row_bcast:15 row_mask:0xa bank_mask:0xf
	v_add_f32_dpp v201, v201, v201 row_bcast:15 row_mask:0xa bank_mask:0xf
	v_add_f32_dpp v202, v202, v202 row_bcast:15 row_mask:0xa bank_mask:0xf
	v_add_f32_dpp v203, v203, v203 row_bcast:15 row_mask:0xa bank_mask:0xf
	v_add_f32_dpp v192, v192, v192 row_bcast:31 row_mask:0xc bank_mask:0xf
	v_add_f32_dpp v193, v193, v193 row_bcast:31 row_mask:0xc bank_mask:0xf
	v_add_f32_dpp v194, v194, v194 row_bcast:31 row_mask:0xc bank_mask:0xf
	v_add_f32_dpp v195, v195, v195 row_bcast:31 row_mask:0xc bank_mask:0xf
	v_add_f32_dpp v196, v196, v196 row_bcast:31 row_mask:0xc bank_mask:0xf
	v_add_f32_dpp v197, v197, v197 row_bcast:31 row_mask:0xc bank_mask:0xf
	v_add_f32_dpp v198, v198, v198 row_bcast:31 row_mask:0xc bank_mask:0xf
	v_add_f32_dpp v199, v199, v199 row_bcast:31 row_mask:0xc bank_mask:0xf
	v_add_f32_dpp v200, v200, v200 row_bcast:31 row_mask:0xc bank_mask:0xf
	v_add_f32_dpp v201, v201, v201 row_bcast:31 row_mask:0xc bank_mask:0xf
	v_add_f32_dpp v202, v202, v202 row_bcast:31 row_mask:0xc bank_mask:0xf
	v_add_f32_dpp v203, v203, v203 row_bcast:31 row_mask:0xc bank_mask:0xf
	s_nop 1
	v_readlane_b32 s18, v192, 63
	v_readlane_b32 s19, v193, 63
	v_readlane_b32 s20, v194, 63
	v_readlane_b32 s21, v195, 63
	v_readlane_b32 s22, v196, 63
	v_readlane_b32 s23, v197, 63
	s_nop 1
	v_writelane_b32 v216, s18, 0
	v_writelane_b32 v216, s19, 1
	v_writelane_b32 v216, s20, 2
	v_writelane_b32 v216, s21, 3
	v_writelane_b32 v216, s22, 4
	v_writelane_b32 v216, s23, 5
	v_readlane_b32 s18, v198, 63
	v_readlane_b32 s19, v199, 63
	v_readlane_b32 s20, v200, 63
	v_readlane_b32 s21, v201, 63
	v_readlane_b32 s22, v202, 63
	v_readlane_b32 s23, v203, 63
	s_nop 1
	v_writelane_b32 v216, s18, 6
	v_writelane_b32 v216, s19, 7
	v_writelane_b32 v216, s20, 8
	v_writelane_b32 v216, s21, 9
	v_writelane_b32 v216, s22, 10
	v_writelane_b32 v216, s23, 11
	v_mov_b32_e32 v46, v216
	v_mov_b32_e32 v35, v216
	v_mov_b32_e32 v37, v216
	v_mov_b32_e32 v39, v216
	v_mov_b32_e32 v41, v216
	v_mov_b32_e32 v43, v216
	v_mov_b32_e32 v19, v216
	v_mov_b32_e32 v45, v216
	v_mov_b32_e32 v48, v216
	v_mov_b32_e32 v20, v216
	v_mov_b32_e32 v22, v216
	v_mov_b32_e32 v24, v216
	v_mov_b32_e32 v34, v217
	v_mov_b32_e32 v36, v217
	v_mov_b32_e32 v38, v217
	v_mov_b32_e32 v40, v217
	v_mov_b32_e32 v42, v217
	v_mov_b32_e32 v18, v217
	v_mov_b32_e32 v44, v217
	v_mov_b32_e32 v47, v217
	v_mov_b32_e32 v49, v217
	v_mov_b32_e32 v21, v217
	v_mov_b32_e32 v23, v217
	v_mov_b32_e32 v25, v217
	s_load_dwordx2 s[18:19], s[0:1], 0x80
	s_load_dwordx2 s[20:21], s[0:1], 0xb0
	s_waitcnt lgkmcnt(0)
	v_cmp_lt_i32_e32 vcc, 7, v68
	s_nop 3
	s_and_saveexec_b64 s[22:23], vcc
	s_xor_b64 s[22:23], exec, s[22:23]
	s_cbranch_execz .LBB0_115
	v_cmp_gt_u32_e32 vcc, 12, v68
	s_and_saveexec_b64 s[24:25], vcc
	s_cbranch_execz .LBB0_114
	v_lshl_add_u64 v[18:19], s[20:21], 0, v[62:63]
	v_add_u32_e32 v66, -8, v68
	v_lshl_add_u64 v[18:19], v[66:67], 2, v[18:19]
	global_load_dword v18, v[18:19], off
	v_add_f32_e32 v19, v48, v49
	s_waitcnt lgkmcnt(2)
	v_add_f32_e32 v20, v20, v21
	v_cmp_eq_u32_e32 vcc, 9, v68
	s_waitcnt lgkmcnt(1)
	v_add_f32_e32 v21, v22, v23
	s_waitcnt lgkmcnt(0)
	v_add_f32_e32 v22, v24, v25
	v_cndmask_b32_e32 v19, v19, v20, vcc
	v_cmp_eq_u32_e32 vcc, 10, v68
	s_mov_b32 s15, 0xc1a00000
	s_nop 0
	v_cndmask_b32_e32 v19, v19, v21, vcc
	v_cmp_eq_u32_e32 vcc, 11, v68
	s_nop 1
	v_cndmask_b32_e32 v19, v19, v22, vcc
	s_waitcnt vmcnt(0)
	v_add_f32_e32 v18, v19, v18
	v_xor_b32_e32 v19, 0x80000000, v18
	v_cmp_ngt_f32_e32 vcc, s15, v18
	s_and_saveexec_b64 s[20:21], vcc
	s_cbranch_execz .LBB0_110
; DEVI float softplus_f(float x) { return x > 20.f ? x : log1pf(expf(x)); }
; template <int WHICH> DEVI void adaln_apply(const P& p, int l, int r, int lane_in, float (&v)[16]) {
;     ...
;             const float lf = -softplus_f(-(d + fb[hd]));
	v_mul_f32_e32 v19, 0xbfb8aa3b, v18
	v_rndne_f32_e32 v20, v19
	s_mov_b32 s15, 0xbfb8aa3b
	v_sub_f32_e32 v21, v19, v20
	v_fma_f32 v19, v18, s15, -v19
	v_fmac_f32_e32 v19, 0xb2a5705f, v18
	v_add_f32_e32 v19, v21, v19
	v_cvt_i32_f32_e32 v20, v20
	v_exp_f32_e32 v19, v19
	s_mov_b32 s15, 0x42ce8ed0
	v_cmp_nlt_f32_e32 vcc, s15, v18
	s_mov_b32 s15, 0xc2b17218
	v_ldexp_f32 v19, v19, v20
	v_cndmask_b32_e32 v19, 0, v19, vcc
	v_cmp_ngt_f32_e32 vcc, s15, v18
	s_mov_b32 s15, 0x3f2aaaab
	s_nop 0
	v_cndmask_b32_e32 v32, v215, v19, vcc
	v_add_f32_e32 v20, 1.0, v32
	v_add_f32_e32 v18, -1.0, v20
	v_sub_f32_e32 v19, v18, v20
	v_add_f32_e32 v19, 1.0, v19
	v_sub_f32_e32 v18, v32, v18
	v_add_f32_e32 v21, v18, v19
	v_frexp_mant_f32_e32 v22, v20
	v_cvt_f64_f32_e32 v[18:19], v20
	v_frexp_exp_i32_f64_e32 v18, v[18:19]
	v_cmp_gt_f32_e32 vcc, s15, v22
	s_mov_b32 s15, 0x3f317218
	s_nop 0
	v_subbrev_co_u32_e32 v26, vcc, 0, v18, vcc
	v_sub_u32_e32 v18, 0, v26
	v_ldexp_f32 v19, v20, v18
	v_add_f32_e32 v20, -1.0, v19
	v_add_f32_e32 v22, 1.0, v19
	v_ldexp_f32 v18, v21, v18
	v_add_f32_e32 v21, 1.0, v20
	v_add_f32_e32 v23, -1.0, v22
	v_sub_f32_e32 v21, v19, v21
	v_sub_f32_e32 v19, v19, v23
	v_add_f32_e32 v21, v18, v21
	v_add_f32_e32 v18, v18, v19
	v_add_f32_e32 v27, v22, v18
	v_rcp_f32_e32 v29, v27
	v_sub_f32_e32 v19, v22, v27
	v_add_f32_e32 v28, v18, v19
	v_add_f32_e32 v19, v20, v21
	v_mul_f32_e32 v31, v19, v29
	v_sub_f32_e32 v18, v20, v19
	v_mul_f32_e32 v20, v27, v31
	v_fma_f32 v22, v31, v27, -v20
	v_fmac_f32_e32 v22, v31, v28
	v_add_f32_e32 v30, v21, v18
	v_add_f32_e32 v18, v20, v22
	v_sub_f32_e32 v21, v19, v18
	v_pk_add_f32 v[24:25], v[18:19], v[20:21] neg_lo:[0,1] neg_hi:[0,1]
	v_mov_b32_e32 v23, v18
	v_pk_add_f32 v[18:19], v[24:25], v[22:23] neg_lo:[0,1] neg_hi:[0,1]
	s_nop 0
	v_add_f32_e32 v19, v30, v19
	v_add_f32_e32 v18, v18, v19
	v_add_f32_e32 v19, v21, v18
	v_mul_f32_e32 v30, v29, v19
	v_mul_f32_e32 v20, v27, v30
	v_fma_f32 v22, v30, v27, -v20
	v_fmac_f32_e32 v22, v30, v28
	v_sub_f32_e32 v21, v21, v19
	v_add_f32_e32 v27, v18, v21
	v_add_f32_e32 v18, v20, v22
	v_sub_f32_e32 v21, v19, v18
	v_pk_add_f32 v[24:25], v[18:19], v[20:21] neg_lo:[0,1] neg_hi:[0,1]
	v_mov_b32_e32 v23, v18
	v_pk_add_f32 v[18:19], v[24:25], v[22:23] neg_lo:[0,1] neg_hi:[0,1]
	s_nop 0
	v_add_f32_e32 v19, v27, v19
	v_add_f32_e32 v18, v18, v19
	v_add_f32_e32 v19, v31, v30
	v_add_f32_e32 v18, v21, v18
	v_sub_f32_e32 v20, v19, v31
	v_mul_f32_e32 v18, v29, v18
	v_sub_f32_e32 v20, v30, v20
	v_add_f32_e32 v20, v20, v18
	v_add_f32_e32 v22, v19, v20
	v_mul_f32_e32 v23, v22, v22
	v_fmamk_f32 v18, v23, 0x3e9b6dac, v212
	v_fmaak_f32 v177, v23, v18, 0x3f2aaada
	v_cvt_f32_i32_e32 v18, v26
	v_sub_f32_e32 v19, v22, v19
	v_sub_f32_e32 v19, v20, v19
	v_ldexp_f32 v24, v19, 1
	v_mul_f32_e32 v19, v22, v23
	v_ldexp_f32 v21, v22, 1
	v_pk_mul_f32 v[22:23], v[18:19], v[176:177]
	s_nop 0
	v_fma_f32 v20, v18, s15, -v22
	v_fmac_f32_e32 v20, 0xb102e308, v18
	v_pk_add_f32 v[18:19], v[22:23], v[20:21]
	s_mov_b32 s15, 0x7f800000
	v_sub_f32_e32 v21, v19, v21
	v_sub_f32_e32 v21, v23, v21
	v_add_f32_e32 v25, v24, v21
	v_mov_b32_e32 v24, v22
	v_pk_add_f32 v[22:23], v[18:19], v[22:23] neg_lo:[0,1] neg_hi:[0,1]
	v_pk_add_f32 v[26:27], v[18:19], v[24:25]
	v_mov_b32_e32 v21, v18
	v_mov_b32_e32 v23, v27
	v_pk_add_f32 v[28:29], v[20:21], v[22:23] neg_lo:[0,1] neg_hi:[0,1]
	v_pk_add_f32 v[20:21], v[20:21], v[22:23]
	v_mov_b32_e32 v24, v25
	v_pk_add_f32 v[22:23], v[20:21], v[18:19] op_sel:[1,0] op_sel_hi:[0,1] neg_lo:[0,1] neg_hi:[0,1]
	v_pk_add_f32 v[30:31], v[26:27], v[22:23] op_sel_hi:[1,0] neg_lo:[0,1] neg_hi:[0,1]
	v_mov_b32_e32 v26, v27
	v_mov_b32_e32 v27, v21
	v_pk_mov_b32 v[22:23], v[18:19], v[22:23] op_sel:[1,0]
	v_mov_b32_e32 v25, v18
	v_pk_add_f32 v[22:23], v[26:27], v[22:23] neg_lo:[0,1] neg_hi:[0,1]
	v_mov_b32_e32 v30, v28
	v_pk_add_f32 v[18:19], v[24:25], v[22:23] neg_lo:[0,1] neg_hi:[0,1]
	v_mov_b32_e32 v29, v21
	v_pk_add_f32 v[22:23], v[30:31], v[18:19]
	v_cmp_neq_f32_e32 vcc, s15, v32
	v_pk_add_f32 v[24:25], v[22:23], v[22:23] op_sel:[0,1] op_sel_hi:[1,0]
	s_mov_b32 s15, 0x33800000
	v_pk_add_f32 v[20:21], v[20:21], v[24:25] op_sel:[1,0] op_sel_hi:[0,1]
	v_mov_b32_e32 v23, v20
	v_pk_add_f32 v[26:27], v[22:23], v[28:29] neg_lo:[0,1] neg_hi:[0,1]
	v_mov_b32_e32 v19, v24
	v_sub_f32_e32 v21, v22, v26
	v_pk_add_f32 v[18:19], v[18:19], v[26:27] neg_lo:[0,1] neg_hi:[0,1]
	v_sub_f32_e32 v21, v28, v21
	v_add_f32_e32 v18, v18, v21
	v_add_f32_e32 v18, v18, v19
	v_add_f32_e32 v18, v20, v18
	v_cndmask_b32_e32 v18, v215, v18, vcc
	v_cmp_lt_f32_e64 vcc, |v32|, s15
	s_nop 1
	v_cndmask_b32_e32 v19, v18, v32, vcc

;     DEVI float* mod() const { return (float*)(ws + WS_MOD); }
;     DEVI float* rstd() const { return (float*)(ws + WS_RSTD); }
;     ...
;     const float* gp = gate2 + (size_t)row_seq(r) * 6144 + 16 * lane;
;     float* xp = x + (size_t)r * D + 16 * lane;
; #pragma unroll
;     for (int q = 0; q < 4; ++q) {
;         float4 xa = *(const float4*)(xp + 4 * q); const float4 ga = *(const float4*)(gp + 4 * q);
;         xa.x += ga.x * o[4 * q]; xa.y += ga.y * o[4 * q + 1]; xa.z += ga.z * o[4 * q + 2]; xa.w += ga.w * o[4 * q + 3];
;         *(float4*)(xp + 4 * q) = xa;
;         o[4 * q] = xa.x; o[4 * q + 1] = xa.y; o[4 * q + 2] = xa.z; o[4 * q + 3] = xa.w;
;     }
; template <int WHICH> DEVI void adaln_apply(const P& p, int l, int r, int lane_in, float (&v)[16]) {
;     ...
;     float ss = 0.f;
; #pragma unroll
;     for (int i = 0; i < 16; ++i) ss += v[i] * v[i];
;     const float rstd = rsqrtf(wave_sum(ss) * (1.f / D) + EPS);
;     const float* md = p.mod() + ((size_t)l * NSEQ + row_seq(r)) * 6144 + 16 * lane;
; #pragma unroll
;     for (int q = 0; q < 4; ++q) {
;         const float4 gg = *(const float4*)(g + 4 * q), sc = *(const float4*)(md + osc + 4 * q), sh = *(const float4*)(md + osh + 4 * q);
.LBB0_1111:
	s_add_i32 s28, s64, s9
	s_mul_i32 s28, s28, s34
	s_add_i32 s28, s28, s48
	s_cmpk_gt_i32 s28, 0x3fff
	s_cbranch_scc1 .LBB0_1110
	v_mov_b32_e32 v114, 0
	s_mov_b32 s29, -16
	s_mov_b32 s30, s65
	v_mov_b32_e32 v115, v114
	v_mov_b32_e32 v120, v114
	v_mov_b32_e32 v121, v114
	v_mov_b32_e32 v118, v114
	v_mov_b32_e32 v119, v114
	v_mov_b32_e32 v128, v114
	v_mov_b32_e32 v129, v114
	v_mov_b32_e32 v130, v114
	v_mov_b32_e32 v131, v114
	v_mov_b32_e32 v122, v114
	v_mov_b32_e32 v123, v114
	v_mov_b32_e32 v124, v114
	v_mov_b32_e32 v125, v114
	v_mov_b32_e32 v126, v114
	v_mov_b32_e32 v127, v114
	s_ashr_i32 s29, s28, 31
	s_lshr_b32 s30, s29, 19
	s_add_i32 s30, s28, s30
	s_ashr_i32 s30, s30, 13
	s_lshl_b64 s[40:41], s[28:29], 12
	s_nop 0
	v_lshl_add_u64 v[16:17], v[112:113], 0, s[40:41]
	global_load_dwordx4 v[30:33], v[16:17], off sc1
	global_load_dwordx4 v[22:25], v[16:17], off offset:16 sc1
	global_load_dwordx4 v[26:29], v[16:17], off offset:32 sc1
	global_load_dwordx4 v[18:21], v[16:17], off offset:48 sc1
	s_waitcnt vmcnt(0)
	s_and_b64 vcc, exec, s[18:19]
	s_cbranch_vccz .LBB0_1110
	v_pk_mul_f32 v[2:3], v[30:31], v[30:31]
	v_pk_mul_f32 v[4:5], v[32:33], v[32:33]
	v_add_f32_e32 v2, v2, v3
	v_add_f32_e32 v2, v4, v2
	v_pk_mul_f32 v[6:7], v[22:23], v[22:23]
	v_add_f32_e32 v2, v5, v2
	v_add_f32_e32 v2, v2, v6
	v_pk_mul_f32 v[8:9], v[24:25], v[24:25]
	v_add_f32_e32 v2, v7, v2
	v_add_f32_e32 v2, v8, v2
	v_pk_mul_f32 v[10:11], v[26:27], v[26:27]
	v_add_f32_e32 v2, v9, v2
	v_add_f32_e32 v2, v2, v10
	v_pk_mul_f32 v[12:13], v[28:29], v[28:29]
	v_add_f32_e32 v2, v11, v2
	v_add_f32_e32 v2, v12, v2
	v_pk_mul_f32 v[14:15], v[18:19], v[18:19]
	v_add_f32_e32 v2, v13, v2
	v_add_f32_e32 v2, v2, v14
	v_pk_mul_f32 v[16:17], v[20:21], v[20:21]
	v_add_f32_e32 v2, v15, v2
	v_add_f32_e32 v2, v16, v2
	v_add_f32_e32 v4, v17, v2
	ds_bpermute_b32 v5, v179, v4
	v_mov_b32_e32 v58, v1
	s_load_dwordx2 s[40:41], s[0:1], 0x48
	s_ashr_i32 s31, s30, 31
	s_waitcnt lgkmcnt(0)
	v_add_f32_e32 v4, v4, v5
	ds_bpermute_b32 v5, v204, v4
	v_lshlrev_b32_e32 v60, 4, v58
	v_ashrrev_i32_e32 v61, 31, v60
	s_add_u32 s40, s40, s20
	s_addc_u32 s41, s41, s21
	s_waitcnt lgkmcnt(0)
	v_add_f32_e32 v4, v4, v5
	ds_bpermute_b32 v5, v205, v4
	v_lshlrev_b64 v[62:63], 2, v[60:61]
	v_lshl_add_u64 v[2:3], s[40:41], 0, v[62:63]
	s_mov_b32 s40, 0x800000
	s_add_u32 s30, s54, s30
	s_waitcnt lgkmcnt(0)
	v_add_f32_e32 v4, v4, v5
	ds_bpermute_b32 v5, v206, v4
	s_addc_u32 s31, s51, s31
	s_mulk_i32 s31, 0x6000
	s_mov_b64 s[42:43], 0x1000
	global_load_dwordx4 v[34:37], v[2:3], off offset:48
	global_load_dwordx4 v[38:41], v[2:3], off offset:32
	global_load_dwordx4 v[50:53], v[2:3], off offset:16
	global_load_dwordx4 v[68:71], v[2:3], off
	s_waitcnt lgkmcnt(0)
	v_add_f32_e32 v4, v4, v5
	ds_bpermute_b32 v5, v207, v4
	s_waitcnt lgkmcnt(0)
	v_add_f32_e32 v4, v4, v5
	ds_bpermute_b32 v5, v208, v4
	s_waitcnt lgkmcnt(0)
	v_add_f32_e32 v4, v4, v5
	v_fmamk_f32 v4, v4, 0x3a800000, v211
	v_cmp_gt_f32_e32 vcc, s40, v4
	v_mul_f32_e32 v5, 0x4b800000, v4
	s_mul_hi_u32 s40, s30, 0x6000
	v_cndmask_b32_e32 v4, v4, v5, vcc
	v_rsq_f32_e32 v4, v4
	s_add_i32 s40, s40, s31
	s_mulk_i32 s30, 0x6000
	s_add_u32 s30, s49, s30
	s_addc_u32 s31, s50, s40
	v_mul_f32_e32 v5, 0x45800000, v4
	v_lshl_add_u64 v[14:15], s[30:31], 0, v[62:63]
	s_movk_i32 s30, 0x1000
	v_cndmask_b32_e32 v59, v4, v5, vcc
	v_add_co_u32_e32 v2, vcc, s30, v14
	v_lshl_add_u64 v[4:5], v[14:15], 0, s[42:43]
	s_nop 0
	v_addc_co_u32_e32 v3, vcc, 0, v15, vcc
	global_load_dwordx4 v[72:75], v[2:3], off
	global_load_dwordx4 v[42:45], v[4:5], off offset:48
	global_load_dwordx4 v[46:49], v[4:5], off offset:32
	global_load_dwordx4 v[54:57], v[4:5], off offset:16
	s_nop 0
	global_load_dwordx4 v[2:5], v[14:15], off offset:48
	global_load_dwordx4 v[6:9], v[14:15], off offset:32
	global_load_dwordx4 v[10:13], v[14:15], off offset:16
	s_nop 0
	global_load_dwordx4 v[14:17], v[14:15], off
	v_mul_f32_e32 v30, v30, v59
	v_mul_f32_e32 v22, v22, v59
	s_lshl_b64 s[30:31], s[28:29], 11
	s_add_u32 s30, s55, s30
	s_addc_u32 s31, s56, s31
	s_waitcnt vmcnt(9)
	v_mul_f32_e32 v22, v22, v50
	s_waitcnt vmcnt(8)
	v_mul_f32_e32 v30, v68, v30
	s_waitcnt vmcnt(7)
	v_add_f32_e32 v64, 1.0, v72
	s_waitcnt vmcnt(0)
	v_fma_f32 v14, v64, v30, v14
	v_mul_f32_e32 v30, v31, v59
	v_mul_f32_e32 v30, v69, v30
	v_add_f32_e32 v31, 1.0, v73
	v_fma_f32 v15, v31, v30, v15
	v_mul_f32_e32 v30, v32, v59
	v_mul_f32_e32 v30, v70, v30
	v_add_f32_e32 v31, 1.0, v74
	v_fma_f32 v16, v31, v30, v16
	v_mul_f32_e32 v30, v33, v59
	v_mul_f32_e32 v30, v71, v30
	v_add_f32_e32 v31, 1.0, v75
	v_fmac_f32_e32 v17, v31, v30
	v_add_f32_e32 v30, 1.0, v54
	v_fma_f32 v50, v22, v30, v10
	v_mul_f32_e32 v10, v23, v59
	v_mul_f32_e32 v10, v10, v51
	v_add_f32_e32 v22, 1.0, v55
	v_fma_f32 v51, v10, v22, v11
	v_mul_f32_e32 v10, v24, v59
	v_mul_f32_e32 v10, v10, v52
	v_add_f32_e32 v11, 1.0, v56
	v_fma_f32 v12, v10, v11, v12
	v_mul_f32_e32 v10, v25, v59
	v_mul_f32_e32 v10, v10, v53
	v_add_f32_e32 v11, 1.0, v57
	v_fmac_f32_e32 v13, v10, v11
	v_mul_f32_e32 v10, v26, v59
	v_mul_f32_e32 v10, v10, v38
	v_add_f32_e32 v11, 1.0, v46
	v_fma_f32 v38, v10, v11, v6
	v_mul_f32_e32 v6, v27, v59
	v_mul_f32_e32 v6, v6, v39
	v_add_f32_e32 v10, 1.0, v47
	v_fma_f32 v39, v6, v10, v7
	v_mul_f32_e32 v6, v28, v59
	v_mul_f32_e32 v6, v6, v40
	v_add_f32_e32 v7, 1.0, v48
	v_fma_f32 v40, v6, v7, v8
	v_mul_f32_e32 v6, v29, v59
	v_mul_f32_e32 v6, v6, v41
	v_add_f32_e32 v7, 1.0, v49
	v_fmac_f32_e32 v9, v6, v7
	v_mul_f32_e32 v6, v18, v59
	v_mul_f32_e32 v6, v6, v34
	v_add_f32_e32 v7, 1.0, v42
	v_fma_f32 v34, v6, v7, v2
	v_mul_f32_e32 v2, v19, v59
	v_mul_f32_e32 v2, v2, v35
	v_add_f32_e32 v6, 1.0, v43
;     DEVI float* rstd() const { return (float*)(ws + WS_RSTD); }
;     DEVI bf16_t* hb() const { return (bf16_t*)(ws + WS_HB); }
; DEVI unsigned pk2bf(float lo, float hi) { unsigned r; asm volatile("v_cvt_pk_bf16_f32 %0, %1, %2" : "=v"(r) : "v"(lo), "v"(hi)); return r; }
; template <int WHICH> DEVI void adaln_apply(const P& p, int l, int r, int lane_in, float (&v)[16]) {
;     ...
;         v[4 * q] = v[4 * q] * rstd * gg.x * (1.f + sc.x) + sh.x; v[4 * q + 1] = v[4 * q + 1] * rstd * gg.y * (1.f + sc.y) + sh.y;
;         v[4 * q + 2] = v[4 * q + 2] * rstd * gg.z * (1.f + sc.z) + sh.z; v[4 * q + 3] = v[4 * q + 3] * rstd * gg.w * (1.f + sc.w) + sh.w;
;     }
;     u32x4_t* ob = (u32x4_t*)(p.hb() + (size_t)r * D + 16 * lane);
;     ob[0] = (u32x4_t){pk2bf(v[0], v[1]), pk2bf(v[2], v[3]), pk2bf(v[4], v[5]), pk2bf(v[6], v[7])};
;     ob[1] = (u32x4_t){pk2bf(v[8], v[9]), pk2bf(v[10], v[11]), pk2bf(v[12], v[13]), pk2bf(v[14], v[15])};
;     ...
;         for (int jj = 0; jj < 12; ++jj) { float a = 0.f;
; #pragma unroll
;             for (int q = 0; q < 4; ++q) { const float4 w = *(const float4*)(ws + (size_t)jj * D + 4 * q); a += v[4 * q] * w.x + v[4 * q + 1] * w.y + v[4 * q + 2] * w.z + v[4 * q + 3] * w.w; }
	v_fma_f32 v35, v2, v6, v3
	v_mul_f32_e32 v2, v20, v59
	v_mul_f32_e32 v2, v2, v36
	v_add_f32_e32 v3, 1.0, v44
	v_fma_f32 v36, v2, v3, v4
	v_mul_f32_e32 v2, v21, v59
	v_mul_f32_e32 v2, v2, v37
	v_add_f32_e32 v3, 1.0, v45
	v_fmac_f32_e32 v5, v2, v3
	v_lshl_add_u64 v[2:3], v[60:61], 1, s[30:31]
	v_cvt_pk_bf16_f32 v18, v14, v15
	v_cvt_pk_bf16_f32 v19, v16, v17
	v_cvt_pk_bf16_f32 v20, v50, v51
	v_cvt_pk_bf16_f32 v21, v12, v13
	global_store_dwordx4 v[2:3], v[18:21], off
	s_nop 1
	v_cvt_pk_bf16_f32 v18, v38, v39
	v_cvt_pk_bf16_f32 v19, v40, v9
	v_cvt_pk_bf16_f32 v20, v34, v35
	v_cvt_pk_bf16_f32 v21, v36, v5
	global_store_dwordx4 v[2:3], v[18:21], off offset:16
	v_mov_b32_e32 v91, 0x14100
	v_lshl_add_u32 v90, v58, 6, v91
	v_mov_b32_e32 v88, 0
	v_mov_b32_e32 v89, 0
	ds_read_b128 v[132:135], v90 offset:0
	ds_read_b128 v[136:139], v90 offset:16
	ds_read_b128 v[140:143], v90 offset:32
	ds_read_b128 v[144:147], v90 offset:48
	ds_read_b128 v[148:151], v90 offset:4096
	ds_read_b128 v[152:155], v90 offset:4112
	ds_read_b128 v[156:159], v90 offset:4128
	ds_read_b128 v[160:163], v90 offset:4144
	ds_read_b128 v[164:167], v90 offset:8192
	ds_read_b128 v[168:171], v90 offset:8208
	ds_read_b128 v[172:175], v90 offset:8224
	ds_read_b128 v[180:183], v90 offset:8240
	ds_read_b128 v[184:187], v90 offset:12288
	ds_read_b128 v[188:191], v90 offset:12304
	ds_read_b128 v[192:195], v90 offset:12320
	ds_read_b128 v[196:199], v90 offset:12336
	s_waitcnt lgkmcnt(0)
	v_mul_f32_e32 v76, v14, v132
	v_mul_f32_e32 v77, v14, v148
	v_mul_f32_e32 v78, v14, v164
	v_mul_f32_e32 v79, v14, v184
	v_fmac_f32_e32 v76, v15, v133
	v_fmac_f32_e32 v77, v15, v149
	v_fmac_f32_e32 v78, v15, v165
	v_fmac_f32_e32 v79, v15, v185
	v_fmac_f32_e32 v76, v16, v134
	v_fmac_f32_e32 v77, v16, v150
	v_fmac_f32_e32 v78, v16, v166
	v_fmac_f32_e32 v79, v16, v186
	v_fmac_f32_e32 v76, v17, v135
	v_fmac_f32_e32 v77, v17, v151
	v_fmac_f32_e32 v78, v17, v167
	v_fmac_f32_e32 v79, v17, v187
	v_fmac_f32_e32 v76, v50, v136
	v_fmac_f32_e32 v77, v50, v152
	v_fmac_f32_e32 v78, v50, v168
	v_fmac_f32_e32 v79, v50, v188
	v_fmac_f32_e32 v76, v51, v137
	v_fmac_f32_e32 v77, v51, v153
	v_fmac_f32_e32 v78, v51, v169
	v_fmac_f32_e32 v79, v51, v189
	v_fmac_f32_e32 v76, v12, v138
	v_fmac_f32_e32 v77, v12, v154
	v_fmac_f32_e32 v78, v12, v170
	v_fmac_f32_e32 v79, v12, v190
	v_fmac_f32_e32 v76, v13, v139
	v_fmac_f32_e32 v77, v13, v155
	v_fmac_f32_e32 v78, v13, v171
	v_fmac_f32_e32 v79, v13, v191
	v_fmac_f32_e32 v76, v38, v140
	v_fmac_f32_e32 v77, v38, v156
	v_fmac_f32_e32 v78, v38, v172
	v_fmac_f32_e32 v79, v38, v192
	v_fmac_f32_e32 v76, v39, v141
	v_fmac_f32_e32 v77, v39, v157
	v_fmac_f32_e32 v78, v39, v173
	v_fmac_f32_e32 v79, v39, v193
	v_fmac_f32_e32 v76, v40, v142
	v_fmac_f32_e32 v77, v40, v158
	v_fmac_f32_e32 v78, v40, v174
	v_fmac_f32_e32 v79, v40, v194
	v_fmac_f32_e32 v76, v9, v143
	v_fmac_f32_e32 v77, v9, v159
	v_fmac_f32_e32 v78, v9, v175
	v_fmac_f32_e32 v79, v9, v195
	v_fmac_f32_e32 v76, v34, v144
	v_fmac_f32_e32 v77, v34, v160
	v_fmac_f32_e32 v78, v34, v180
	v_fmac_f32_e32 v79, v34, v196
	v_fmac_f32_e32 v76, v35, v145
	v_fmac_f32_e32 v77, v35, v161
	v_fmac_f32_e32 v78, v35, v181
	v_fmac_f32_e32 v79, v35, v197
	v_fmac_f32_e32 v76, v36, v146
	v_fmac_f32_e32 v77, v36, v162
	v_fmac_f32_e32 v78, v36, v182
	v_fmac_f32_e32 v79, v36, v198
	v_fmac_f32_e32 v76, v5, v147
	v_fmac_f32_e32 v77, v5, v163
	v_fmac_f32_e32 v78, v5, v183
	v_fmac_f32_e32 v79, v5, v199
	ds_read_b128 v[132:135], v90 offset:16384
	ds_read_b128 v[136:139], v90 offset:16400
	ds_read_b128 v[140:143], v90 offset:16416
	ds_read_b128 v[144:147], v90 offset:16432
	ds_read_b128 v[148:151], v90 offset:20480
	ds_read_b128 v[152:155], v90 offset:20496
	ds_read_b128 v[156:159], v90 offset:20512
	ds_read_b128 v[160:163], v90 offset:20528
	ds_read_b128 v[164:167], v90 offset:24576
	ds_read_b128 v[168:171], v90 offset:24592
	ds_read_b128 v[172:175], v90 offset:24608
	ds_read_b128 v[180:183], v90 offset:24624
	ds_read_b128 v[184:187], v90 offset:28672
	ds_read_b128 v[188:191], v90 offset:28688
	ds_read_b128 v[192:195], v90 offset:28704
	ds_read_b128 v[196:199], v90 offset:28720
	s_waitcnt lgkmcnt(0)
	v_mul_f32_e32 v80, v14, v132
	v_mul_f32_e32 v81, v14, v148
	v_mul_f32_e32 v82, v14, v164
	v_mul_f32_e32 v83, v14, v184
	v_fmac_f32_e32 v80, v15, v133
	v_fmac_f32_e32 v81, v15, v149
	v_fmac_f32_e32 v82, v15, v165
	v_fmac_f32_e32 v83, v15, v185
	v_fmac_f32_e32 v80, v16, v134
	v_fmac_f32_e32 v81, v16, v150
	v_fmac_f32_e32 v82, v16, v166
	v_fmac_f32_e32 v83, v16, v186
	v_fmac_f32_e32 v80, v17, v135
	v_fmac_f32_e32 v81, v17, v151
	v_fmac_f32_e32 v82, v17, v167
	v_fmac_f32_e32 v83, v17, v187
	v_fmac_f32_e32 v80, v50, v136
	v_fmac_f32_e32 v81, v50, v152
	v_fmac_f32_e32 v82, v50, v168
	v_fmac_f32_e32 v83, v50, v188
	v_fmac_f32_e32 v80, v51, v137
	v_fmac_f32_e32 v81, v51, v153
	v_fmac_f32_e32 v82, v51, v169
	v_fmac_f32_e32 v83, v51, v189
	v_fmac_f32_e32 v80, v12, v138
	v_fmac_f32_e32 v81, v12, v154
	v_fmac_f32_e32 v82, v12, v170
	v_fmac_f32_e32 v83, v12, v190
	v_fmac_f32_e32 v80, v13, v139
	v_fmac_f32_e32 v81, v13, v155
	v_fmac_f32_e32 v82, v13, v171
	v_fmac_f32_e32 v83, v13, v191
	v_fmac_f32_e32 v80, v38, v140
	v_fmac_f32_e32 v81, v38, v156
	v_fmac_f32_e32 v82, v38, v172
	v_fmac_f32_e32 v83, v38, v192
	v_fmac_f32_e32 v80, v39, v141
	v_fmac_f32_e32 v81, v39, v157
	v_fmac_f32_e32 v82, v39, v173
	v_fmac_f32_e32 v83, v39, v193
	v_fmac_f32_e32 v80, v40, v142
	v_fmac_f32_e32 v81, v40, v158
	v_fmac_f32_e32 v82, v40, v174
	v_fmac_f32_e32 v83, v40, v194
	v_fmac_f32_e32 v80, v9, v143
	v_fmac_f32_e32 v81, v9, v159
	v_fmac_f32_e32 v82, v9, v175
	v_fmac_f32_e32 v83, v9, v195
	v_fmac_f32_e32 v80, v34, v144
	v_fmac_f32_e32 v81, v34, v160
	v_fmac_f32_e32 v82, v34, v180
	v_fmac_f32_e32 v83, v34, v196
	v_fmac_f32_e32 v80, v35, v145
	v_fmac_f32_e32 v81, v35, v161
	v_fmac_f32_e32 v82, v35, v181
	v_fmac_f32_e32 v83, v35, v197
	v_fmac_f32_e32 v80, v36, v146
	v_fmac_f32_e32 v81, v36, v162
	v_fmac_f32_e32 v82, v36, v182
	v_fmac_f32_e32 v83, v36, v198
	v_fmac_f32_e32 v80, v5, v147
	v_fmac_f32_e32 v81, v5, v163
	v_fmac_f32_e32 v82, v5, v183
	v_fmac_f32_e32 v83, v5, v199
	ds_read_b128 v[132:135], v90 offset:32768
	ds_read_b128 v[136:139], v90 offset:32784
	ds_read_b128 v[140:143], v90 offset:32800
	ds_read_b128 v[144:147], v90 offset:32816
	ds_read_b128 v[148:151], v90 offset:36864
	ds_read_b128 v[152:155], v90 offset:36880
	ds_read_b128 v[156:159], v90 offset:36896
	ds_read_b128 v[160:163], v90 offset:36912
	ds_read_b128 v[164:167], v90 offset:40960
	ds_read_b128 v[168:171], v90 offset:40976
	ds_read_b128 v[172:175], v90 offset:40992
	ds_read_b128 v[180:183], v90 offset:41008
	ds_read_b128 v[184:187], v90 offset:45056
	ds_read_b128 v[188:191], v90 offset:45072
	ds_read_b128 v[192:195], v90 offset:45088
	ds_read_b128 v[196:199], v90 offset:45104
	s_waitcnt lgkmcnt(0)
; DEVI float wave_sum(float v) {
; #pragma unroll
;     for (int o = 1; o < 64; o <<= 1) v += __shfl_xor(v, o);
;     return v;
; template <int WHICH> DEVI void adaln_apply(const P& p, int l, int r, int lane_in, float (&v)[16]) {
;     ...
;         for (int jj = 0; jj < 12; ++jj) { float a = 0.f;
; #pragma unroll
;             for (int q = 0; q < 4; ++q) { const float4 w = *(const float4*)(ws + (size_t)jj * D + 4 * q); a += v[4 * q] * w.x + v[4 * q + 1] * w.y + v[4 * q + 2] * w.z + v[4 * q + 3] * w.w; }
;             dot[jj] = wave_sum(a); }
	v_mul_f32_e32 v84, v14, v132
	v_mul_f32_e32 v85, v14, v148
	v_mul_f32_e32 v86, v14, v164
	v_mul_f32_e32 v87, v14, v184
	v_fmac_f32_e32 v84, v15, v133
	v_fmac_f32_e32 v85, v15, v149
	v_fmac_f32_e32 v86, v15, v165
	v_fmac_f32_e32 v87, v15, v185
	v_fmac_f32_e32 v84, v16, v134
	v_fmac_f32_e32 v85, v16, v150
	v_fmac_f32_e32 v86, v16, v166
	v_fmac_f32_e32 v87, v16, v186
	v_fmac_f32_e32 v84, v17, v135
	v_fmac_f32_e32 v85, v17, v151
	v_fmac_f32_e32 v86, v17, v167
	v_fmac_f32_e32 v87, v17, v187
	v_fmac_f32_e32 v84, v50, v136
	v_fmac_f32_e32 v85, v50, v152
	v_fmac_f32_e32 v86, v50, v168
	v_fmac_f32_e32 v87, v50, v188
	v_fmac_f32_e32 v84, v51, v137
	v_fmac_f32_e32 v85, v51, v153
	v_fmac_f32_e32 v86, v51, v169
	v_fmac_f32_e32 v87, v51, v189
	v_fmac_f32_e32 v84, v12, v138
	v_fmac_f32_e32 v85, v12, v154
	v_fmac_f32_e32 v86, v12, v170
	v_fmac_f32_e32 v87, v12, v190
	v_fmac_f32_e32 v84, v13, v139
	v_fmac_f32_e32 v85, v13, v155
	v_fmac_f32_e32 v86, v13, v171
	v_fmac_f32_e32 v87, v13, v191
	v_fmac_f32_e32 v84, v38, v140
	v_fmac_f32_e32 v85, v38, v156
	v_fmac_f32_e32 v86, v38, v172
	v_fmac_f32_e32 v87, v38, v192
	v_fmac_f32_e32 v84, v39, v141
	v_fmac_f32_e32 v85, v39, v157
	v_fmac_f32_e32 v86, v39, v173
	v_fmac_f32_e32 v87, v39, v193
	v_fmac_f32_e32 v84, v40, v142
	v_fmac_f32_e32 v85, v40, v158
	v_fmac_f32_e32 v86, v40, v174
	v_fmac_f32_e32 v87, v40, v194
	v_fmac_f32_e32 v84, v9, v143
	v_fmac_f32_e32 v85, v9, v159
	v_fmac_f32_e32 v86, v9, v175
	v_fmac_f32_e32 v87, v9, v195
	v_fmac_f32_e32 v84, v34, v144
	v_fmac_f32_e32 v85, v34, v160
	v_fmac_f32_e32 v86, v34, v180
	v_fmac_f32_e32 v87, v34, v196
	v_fmac_f32_e32 v84, v35, v145
	v_fmac_f32_e32 v85, v35, v161
	v_fmac_f32_e32 v86, v35, v181
	v_fmac_f32_e32 v87, v35, v197
	v_fmac_f32_e32 v84, v36, v146
	v_fmac_f32_e32 v85, v36, v162
	v_fmac_f32_e32 v86, v36, v182
	v_fmac_f32_e32 v87, v36, v198
	v_fmac_f32_e32 v84, v5, v147
	v_fmac_f32_e32 v85, v5, v163
	v_fmac_f32_e32 v86, v5, v183
	v_fmac_f32_e32 v87, v5, v199
	s_nop 1
	v_add_f32_dpp v76, v76, v76 quad_perm:[1,0,3,2] row_mask:0xf bank_mask:0xf
	v_add_f32_dpp v77, v77, v77 quad_perm:[1,0,3,2] row_mask:0xf bank_mask:0xf
	v_add_f32_dpp v78, v78, v78 quad_perm:[1,0,3,2] row_mask:0xf bank_mask:0xf
	v_add_f32_dpp v79, v79, v79 quad_perm:[1,0,3,2] row_mask:0xf bank_mask:0xf
	v_add_f32_dpp v80, v80, v80 quad_perm:[1,0,3,2] row_mask:0xf bank_mask:0xf
	v_add_f32_dpp v81, v81, v81 quad_perm:[1,0,3,2] row_mask:0xf bank_mask:0xf
	v_add_f32_dpp v82, v82, v82 quad_perm:[1,0,3,2] row_mask:0xf bank_mask:0xf
	v_add_f32_dpp v83, v83, v83 quad_perm:[1,0,3,2] row_mask:0xf bank_mask:0xf
	v_add_f32_dpp v84, v84, v84 quad_perm:[1,0,3,2] row_mask:0xf bank_mask:0xf
	v_add_f32_dpp v85, v85, v85 quad_perm:[1,0,3,2] row_mask:0xf bank_mask:0xf
	v_add_f32_dpp v86, v86, v86 quad_perm:[1,0,3,2] row_mask:0xf bank_mask:0xf
	v_add_f32_dpp v87, v87, v87 quad_perm:[1,0,3,2] row_mask:0xf bank_mask:0xf
	v_add_f32_dpp v76, v76, v76 quad_perm:[2,3,0,1] row_mask:0xf bank_mask:0xf
	v_add_f32_dpp v77, v77, v77 quad_perm:[2,3,0,1] row_mask:0xf bank_mask:0xf
	v_add_f32_dpp v78, v78, v78 quad_perm:[2,3,0,1] row_mask:0xf bank_mask:0xf
	v_add_f32_dpp v79, v79, v79 quad_perm:[2,3,0,1] row_mask:0xf bank_mask:0xf
	v_add_f32_dpp v80, v80, v80 quad_perm:[2,3,0,1] row_mask:0xf bank_mask:0xf
	v_add_f32_dpp v81, v81, v81 quad_perm:[2,3,0,1] row_mask:0xf bank_mask:0xf
	v_add_f32_dpp v82, v82, v82 quad_perm:[2,3,0,1] row_mask:0xf bank_mask:0xf
	v_add_f32_dpp v83, v83, v83 quad_perm:[2,3,0,1] row_mask:0xf bank_mask:0xf
	v_add_f32_dpp v84, v84, v84 quad_perm:[2,3,0,1] row_mask:0xf bank_mask:0xf
	v_add_f32_dpp v85, v85, v85 quad_perm:[2,3,0,1] row_mask:0xf bank_mask:0xf
	v_add_f32_dpp v86, v86, v86 quad_perm:[2,3,0,1] row_mask:0xf bank_mask:0xf
	v_add_f32_dpp v87, v87, v87 quad_perm:[2,3,0,1] row_mask:0xf bank_mask:0xf
	v_add_f32_dpp v76, v76, v76 row_half_mirror row_mask:0xf bank_mask:0xf
	v_add_f32_dpp v77, v77, v77 row_half_mirror row_mask:0xf bank_mask:0xf
	v_add_f32_dpp v78, v78, v78 row_half_mirror row_mask:0xf bank_mask:0xf
	v_add_f32_dpp v79, v79, v79 row_half_mirror row_mask:0xf bank_mask:0xf
	v_add_f32_dpp v80, v80, v80 row_half_mirror row_mask:0xf bank_mask:0xf
	v_add_f32_dpp v81, v81, v81 row_half_mirror row_mask:0xf bank_mask:0xf
	v_add_f32_dpp v82, v82, v82 row_half_mirror row_mask:0xf bank_mask:0xf
	v_add_f32_dpp v83, v83, v83 row_half_mirror row_mask:0xf bank_mask:0xf
	v_add_f32_dpp v84, v84, v84 row_half_mirror row_mask:0xf bank_mask:0xf
	v_add_f32_dpp v85, v85, v85 row_half_mirror row_mask:0xf bank_mask:0xf
	v_add_f32_dpp v86, v86, v86 row_half_mirror row_mask:0xf bank_mask:0xf
	v_add_f32_dpp v87, v87, v87 row_half_mirror row_mask:0xf bank_mask:0xf
	v_add_f32_dpp v76, v76, v76 row_mirror row_mask:0xf bank_mask:0xf
	v_add_f32_dpp v77, v77, v77 row_mirror row_mask:0xf bank_mask:0xf
	v_add_f32_dpp v78, v78, v78 row_mirror row_mask:0xf bank_mask:0xf
	v_add_f32_dpp v79, v79, v79 row_mirror row_mask:0xf bank_mask:0xf
	v_add_f32_dpp v80, v80, v80 row_mirror row_mask:0xf bank_mask:0xf
	v_add_f32_dpp v81, v81, v81 row_mirror row_mask:0xf bank_mask:0xf
	v_add_f32_dpp v82, v82, v82 row_mirror row_mask:0xf bank_mask:0xf
	v_add_f32_dpp v83, v83, v83 row_mirror row_mask:0xf bank_mask:0xf
	v_add_f32_dpp v84, v84, v84 row_mirror row_mask:0xf bank_mask:0xf
	v_add_f32_dpp v85, v85, v85 row_mirror row_mask:0xf bank_mask:0xf
	v_add_f32_dpp v86, v86, v86 row_mirror row_mask:0xf bank_mask:0xf
	v_add_f32_dpp v87, v87, v87 row_mirror row_mask:0xf bank_mask:0xf
	v_add_f32_dpp v76, v76, v76 row_bcast:15 row_mask:0xa bank_mask:0xf
	v_add_f32_dpp v77, v77, v77 row_bcast:15 row_mask:0xa bank_mask:0xf
;     DEVI float* dt() const { return (float*)(ws + WS_DT); }
;     DEVI float* logf() const { return (float*)(ws + WS_LOGF); }
; DEVI float softplus_f(float x) { return x > 20.f ? x : log1pf(expf(x)); }
; template <int WHICH> DEVI void adaln_apply(const P& p, int l, int r, int lane_in, float (&v)[16]) {
;     ...
;         for (int jj = 0; jj < 12; ++jj) { float a = 0.f;
; #pragma unroll
;             for (int q = 0; q < 4; ++q) { const float4 w = *(const float4*)(ws + (size_t)jj * D + 4 * q); a += v[4 * q] * w.x + v[4 * q + 1] * w.y + v[4 * q + 2] * w.z + v[4 * q + 3] * w.w; }
;             dot[jj] = wave_sum(a); }
;         if (lane < 8) {
;             float d = dot[0];
; #pragma unroll
;             for (int jj = 1; jj < 8; ++jj) d = (lane == jj) ? dot[jj] : d;
;             p.dt()[(size_t)r * 8 + lane] = softplus_f(d + dtb[lane]);
;         } else if (lane < 12) {
;             const int hd = lane - 8; float d = dot[8];
; #pragma unroll
;             for (int jj = 9; jj < 12; ++jj) d = (lane == jj) ? dot[jj] : d;
;             const float lf = -softplus_f(-(d + fb[hd]));
;             p.logf()[(size_t)r * 4 + hd] = lf;
;             if (r < M_P) p.out[OUT_LFP + ((size_t)l * M_P + r) * 4 + hd] = lf; else p.out[OUT_LFS + ((size_t)l * M_S + (r - M_P)) * 4 + hd] = lf;
	v_add_f32_dpp v78, v78, v78 row_bcast:15 row_mask:0xa bank_mask:0xf
	v_add_f32_dpp v79, v79, v79 row_bcast:15 row_mask:0xa bank_mask:0xf
	v_add_f32_dpp v80, v80, v80 row_bcast:15 row_mask:0xa bank_mask:0xf
	v_add_f32_dpp v81, v81, v81 row_bcast:15 row_mask:0xa bank_mask:0xf
	v_add_f32_dpp v82, v82, v82 row_bcast:15 row_mask:0xa bank_mask:0xf
	v_add_f32_dpp v83, v83, v83 row_bcast:15 row_mask:0xa bank_mask:0xf
	v_add_f32_dpp v84, v84, v84 row_bcast:15 row_mask:0xa bank_mask:0xf
	v_add_f32_dpp v85, v85, v85 row_bcast:15 row_mask:0xa bank_mask:0xf
	v_add_f32_dpp v86, v86, v86 row_bcast:15 row_mask:0xa bank_mask:0xf
	v_add_f32_dpp v87, v87, v87 row_bcast:15 row_mask:0xa bank_mask:0xf
	v_add_f32_dpp v76, v76, v76 row_bcast:31 row_mask:0xc bank_mask:0xf
	v_add_f32_dpp v77, v77, v77 row_bcast:31 row_mask:0xc bank_mask:0xf
	v_add_f32_dpp v78, v78, v78 row_bcast:31 row_mask:0xc bank_mask:0xf
	v_add_f32_dpp v79, v79, v79 row_bcast:31 row_mask:0xc bank_mask:0xf
	v_add_f32_dpp v80, v80, v80 row_bcast:31 row_mask:0xc bank_mask:0xf
	v_add_f32_dpp v81, v81, v81 row_bcast:31 row_mask:0xc bank_mask:0xf
	v_add_f32_dpp v82, v82, v82 row_bcast:31 row_mask:0xc bank_mask:0xf
	v_add_f32_dpp v83, v83, v83 row_bcast:31 row_mask:0xc bank_mask:0xf
	v_add_f32_dpp v84, v84, v84 row_bcast:31 row_mask:0xc bank_mask:0xf
	v_add_f32_dpp v85, v85, v85 row_bcast:31 row_mask:0xc bank_mask:0xf
	v_add_f32_dpp v86, v86, v86 row_bcast:31 row_mask:0xc bank_mask:0xf
	v_add_f32_dpp v87, v87, v87 row_bcast:31 row_mask:0xc bank_mask:0xf
	s_nop 1
	v_readlane_b32 s30, v76, 63
	v_readlane_b32 s31, v77, 63
	v_readlane_b32 s40, v78, 63
	v_readlane_b32 s41, v79, 63
	v_readlane_b32 s42, v80, 63
	v_readlane_b32 s43, v81, 63
	s_nop 1
	v_writelane_b32 v88, s30, 0
	v_writelane_b32 v88, s31, 1
	v_writelane_b32 v88, s40, 2
	v_writelane_b32 v88, s41, 3
	v_writelane_b32 v88, s42, 4
	v_writelane_b32 v88, s43, 5
	v_readlane_b32 s30, v82, 63
	v_readlane_b32 s31, v83, 63
	v_readlane_b32 s40, v84, 63
	v_readlane_b32 s41, v85, 63
	v_readlane_b32 s42, v86, 63
	v_readlane_b32 s43, v87, 63
	s_nop 1
	v_writelane_b32 v88, s30, 6
	v_writelane_b32 v88, s31, 7
	v_writelane_b32 v88, s40, 8
	v_writelane_b32 v88, s41, 9
	v_writelane_b32 v88, s42, 10
	v_writelane_b32 v88, s43, 11
	v_mov_b32_e32 v4, v88
	v_mov_b32_e32 v37, v88
	v_mov_b32_e32 v42, v88
	v_mov_b32_e32 v44, v88
	v_mov_b32_e32 v46, v88
	v_mov_b32_e32 v48, v88
	v_mov_b32_e32 v52, v88
	v_mov_b32_e32 v54, v88
	v_mov_b32_e32 v56, v88
	v_mov_b32_e32 v6, v88
	v_mov_b32_e32 v10, v88
	v_mov_b32_e32 v2, v88
	v_mov_b32_e32 v8, v89
	v_mov_b32_e32 v41, v89
	v_mov_b32_e32 v43, v89
	v_mov_b32_e32 v45, v89
	v_mov_b32_e32 v47, v89
	v_mov_b32_e32 v49, v89
	v_mov_b32_e32 v53, v89
	v_mov_b32_e32 v55, v89
	v_mov_b32_e32 v57, v89
	v_mov_b32_e32 v7, v89
	v_mov_b32_e32 v11, v89
	v_mov_b32_e32 v3, v89
	s_load_dwordx2 s[30:31], s[0:1], 0x80
	s_load_dwordx2 s[40:41], s[0:1], 0xb0
	s_waitcnt lgkmcnt(0)
	v_cmp_lt_i32_e32 vcc, 7, v58
	s_nop 3
	s_and_saveexec_b64 s[42:43], vcc
	s_xor_b64 s[42:43], exec, s[42:43]
	s_cbranch_execz .LBB0_1121
	v_cmp_gt_u32_e32 vcc, 12, v58
	s_and_saveexec_b64 s[44:45], vcc
	s_cbranch_execz .LBB0_1120
	s_add_u32 s40, s40, s24
	s_addc_u32 s41, s41, s25
	v_add_u32_e32 v66, -8, v58
	v_lshl_add_u64 v[4:5], v[66:67], 2, s[40:41]
	global_load_dword v4, v[4:5], off
	v_add_f32_e32 v5, v56, v57
	v_add_f32_e32 v6, v6, v7
	v_cmp_eq_u32_e32 vcc, 9, v58
	v_add_f32_e32 v7, v10, v11
	s_waitcnt lgkmcnt(0)
	v_add_f32_e32 v2, v2, v3
	v_cndmask_b32_e32 v3, v5, v6, vcc
	v_cmp_eq_u32_e32 vcc, 10, v58
	s_mov_b32 s40, 0xc1a00000
	s_nop 0
	v_cndmask_b32_e32 v3, v3, v7, vcc
	v_cmp_eq_u32_e32 vcc, 11, v58
	s_nop 1
	v_cndmask_b32_e32 v2, v3, v2, vcc
	s_waitcnt vmcnt(0)
	v_add_f32_e32 v2, v2, v4
	v_xor_b32_e32 v3, 0x80000000, v2
	v_cmp_ngt_f32_e32 vcc, s40, v2
	s_and_saveexec_b64 s[40:41], vcc
	s_cbranch_execz .LBB0_1119
;     DEVI float* logf() const { return (float*)(ws + WS_LOGF); }
; DEVI float softplus_f(float x) { return x > 20.f ? x : log1pf(expf(x)); }
; template <int WHICH> DEVI void adaln_apply(const P& p, int l, int r, int lane_in, float (&v)[16]) {
;     ...
;         } else if (lane < 12) {
;             const int hd = lane - 8; float d = dot[8];
; #pragma unroll
;             for (int jj = 9; jj < 12; ++jj) d = (lane == jj) ? dot[jj] : d;
;             const float lf = -softplus_f(-(d + fb[hd]));
;             p.logf()[(size_t)r * 4 + hd] = lf;
	v_mul_f32_e32 v3, 0xbfb8aa3b, v2
	v_rndne_f32_e32 v4, v3
	s_mov_b32 s66, 0xbfb8aa3b
	v_sub_f32_e32 v5, v3, v4
	v_fma_f32 v3, v2, s66, -v3
	v_fmac_f32_e32 v3, 0xb2a5705f, v2
	v_add_f32_e32 v3, v5, v3
	v_cvt_i32_f32_e32 v4, v4
	v_exp_f32_e32 v3, v3
	s_mov_b32 s66, 0x42ce8ed0
	v_cmp_nlt_f32_e32 vcc, s66, v2
	s_mov_b32 s66, 0xc2b17218
	v_ldexp_f32 v3, v3, v4
	v_cndmask_b32_e32 v3, 0, v3, vcc
	v_cmp_ngt_f32_e32 vcc, s66, v2
	s_mov_b32 s66, 0x3f2aaaab
	s_nop 0
	v_cndmask_b32_e32 v16, v215, v3, vcc
	v_add_f32_e32 v4, 1.0, v16
	v_add_f32_e32 v2, -1.0, v4
	v_sub_f32_e32 v3, v2, v4
	v_add_f32_e32 v3, 1.0, v3
	v_sub_f32_e32 v2, v16, v2
	v_add_f32_e32 v5, v2, v3
	v_frexp_mant_f32_e32 v6, v4
	v_cvt_f64_f32_e32 v[2:3], v4
	v_frexp_exp_i32_f64_e32 v2, v[2:3]
	v_cmp_gt_f32_e32 vcc, s66, v6
	s_mov_b32 s66, 0x3f317218
	s_nop 0
	v_subbrev_co_u32_e32 v10, vcc, 0, v2, vcc
	v_sub_u32_e32 v2, 0, v10
	v_ldexp_f32 v3, v4, v2
	v_add_f32_e32 v4, -1.0, v3
	v_add_f32_e32 v6, 1.0, v3
	v_ldexp_f32 v2, v5, v2
	v_add_f32_e32 v5, 1.0, v4
	v_add_f32_e32 v7, -1.0, v6
	v_sub_f32_e32 v5, v3, v5
	v_sub_f32_e32 v3, v3, v7
	v_add_f32_e32 v5, v2, v5
	v_add_f32_e32 v2, v2, v3
	v_add_f32_e32 v11, v6, v2
	v_rcp_f32_e32 v13, v11
	v_sub_f32_e32 v3, v6, v11
	v_add_f32_e32 v12, v2, v3
	v_add_f32_e32 v3, v4, v5
	v_mul_f32_e32 v15, v3, v13
	v_sub_f32_e32 v2, v4, v3
	v_mul_f32_e32 v4, v11, v15
	v_fma_f32 v6, v15, v11, -v4
	v_fmac_f32_e32 v6, v15, v12
	v_add_f32_e32 v14, v5, v2
	v_add_f32_e32 v2, v4, v6
	v_sub_f32_e32 v5, v3, v2
	v_pk_add_f32 v[8:9], v[2:3], v[4:5] neg_lo:[0,1] neg_hi:[0,1]
	v_mov_b32_e32 v7, v2
	v_pk_add_f32 v[2:3], v[8:9], v[6:7] neg_lo:[0,1] neg_hi:[0,1]
	s_nop 0
	v_add_f32_e32 v3, v14, v3
	v_add_f32_e32 v2, v2, v3
	v_add_f32_e32 v3, v5, v2
	v_mul_f32_e32 v14, v13, v3
	v_mul_f32_e32 v4, v11, v14
	v_fma_f32 v6, v14, v11, -v4
	v_fmac_f32_e32 v6, v14, v12
	v_sub_f32_e32 v5, v5, v3
	v_add_f32_e32 v11, v2, v5
	v_add_f32_e32 v2, v4, v6
	v_sub_f32_e32 v5, v3, v2
	v_pk_add_f32 v[8:9], v[2:3], v[4:5] neg_lo:[0,1] neg_hi:[0,1]
	v_mov_b32_e32 v7, v2
	v_pk_add_f32 v[2:3], v[8:9], v[6:7] neg_lo:[0,1] neg_hi:[0,1]
	s_nop 0
	v_add_f32_e32 v3, v11, v3
	v_add_f32_e32 v2, v2, v3
	v_add_f32_e32 v3, v15, v14
	v_add_f32_e32 v2, v5, v2
	v_sub_f32_e32 v4, v3, v15
	v_mul_f32_e32 v2, v13, v2
	v_sub_f32_e32 v4, v14, v4
	v_add_f32_e32 v4, v4, v2
	v_add_f32_e32 v6, v3, v4
	v_mul_f32_e32 v7, v6, v6
	v_fmamk_f32 v2, v7, 0x3e9b6dac, v212
	v_fmaak_f32 v177, v7, v2, 0x3f2aaada
	v_cvt_f32_i32_e32 v2, v10
	v_sub_f32_e32 v3, v6, v3
	v_sub_f32_e32 v3, v4, v3
	v_ldexp_f32 v8, v3, 1
	v_mul_f32_e32 v3, v6, v7
	v_ldexp_f32 v5, v6, 1
	v_pk_mul_f32 v[6:7], v[2:3], v[176:177]
	s_nop 0
	v_fma_f32 v4, v2, s66, -v6
	v_fmac_f32_e32 v4, 0xb102e308, v2
	v_pk_add_f32 v[2:3], v[6:7], v[4:5]
	s_mov_b32 s66, 0x7f800000
	v_sub_f32_e32 v5, v3, v5
	v_sub_f32_e32 v5, v7, v5
	v_add_f32_e32 v9, v8, v5
	v_mov_b32_e32 v8, v6
	v_pk_add_f32 v[6:7], v[2:3], v[6:7] neg_lo:[0,1] neg_hi:[0,1]
	v_pk_add_f32 v[10:11], v[2:3], v[8:9]
	v_mov_b32_e32 v5, v2
	v_mov_b32_e32 v7, v11
	v_pk_add_f32 v[12:13], v[4:5], v[6:7] neg_lo:[0,1] neg_hi:[0,1]
	v_pk_add_f32 v[4:5], v[4:5], v[6:7]
	v_mov_b32_e32 v8, v9
	v_pk_add_f32 v[6:7], v[4:5], v[2:3] op_sel:[1,0] op_sel_hi:[0,1] neg_lo:[0,1] neg_hi:[0,1]
	v_pk_add_f32 v[14:15], v[10:11], v[6:7] op_sel_hi:[1,0] neg_lo:[0,1] neg_hi:[0,1]
	v_mov_b32_e32 v10, v11
	v_mov_b32_e32 v11, v5
	v_pk_mov_b32 v[6:7], v[2:3], v[6:7] op_sel:[1,0]
	v_mov_b32_e32 v9, v2
	v_pk_add_f32 v[6:7], v[10:11], v[6:7] neg_lo:[0,1] neg_hi:[0,1]
	v_mov_b32_e32 v14, v12
	v_pk_add_f32 v[2:3], v[8:9], v[6:7] neg_lo:[0,1] neg_hi:[0,1]
	v_mov_b32_e32 v13, v5
	v_pk_add_f32 v[6:7], v[14:15], v[2:3]
	v_cmp_neq_f32_e32 vcc, s66, v16
	v_pk_add_f32 v[8:9], v[6:7], v[6:7] op_sel:[0,1] op_sel_hi:[1,0]
	s_mov_b32 s66, 0x33800000
	v_pk_add_f32 v[4:5], v[4:5], v[8:9] op_sel:[1,0] op_sel_hi:[0,1]
	v_mov_b32_e32 v7, v4
	v_pk_add_f32 v[10:11], v[6:7], v[12:13] neg_lo:[0,1] neg_hi:[0,1]
	v_mov_b32_e32 v3, v8
	v_sub_f32_e32 v5, v6, v10
	v_pk_add_f32 v[2:3], v[2:3], v[10:11] neg_lo:[0,1] neg_hi:[0,1]
	v_sub_f32_e32 v5, v12, v5
	v_add_f32_e32 v2, v2, v5
	v_add_f32_e32 v2, v2, v3
	v_add_f32_e32 v2, v4, v2
	v_cndmask_b32_e32 v2, v215, v2, vcc
	v_cmp_lt_f32_e64 vcc, |v16|, s66
	s_nop 1
	v_cndmask_b32_e32 v3, v2, v16, vcc
